# gdn chunk transpose_reduce64: xor-32/16/8/2/1 lane exchanges via permlane swap / DPP instead of ds_bpermute + wait
# speedup vs baseline: 1.0056x; 1.0033x over previous
; __device__ __forceinline__ float bf2f(u16 h) { return __uint_as_float(((unsigned)h) << 16); }
; __device__ __forceinline__ float siluf_(float x) { return x * __builtin_amdgcn_rcpf(1.f + __expf(-x)); }
; __device__ __forceinline__ void gdn_chunk_item(const Params& p, int item, char* smem) {
;     ...
;     __syncthreads();
;     {
;       const int col = type * 512 + h * 128 + c;
;       const float w0 = p.conv_w[col], w1 = p.conv_w[1536 + col], w2 = p.conv_w[3072 + col], w3 = p.conv_w[4608 + col];
;       const u16* tp = tile + type * 128 + c;
;       float x0 = bf2f(tp[0]), x1 = bf2f(tp[384]), x2 = bf2f(tp[768]);
; #pragma unroll
;       for (int t = 0; t < 64; t++) {
;         float x3 = bf2f(tp[(t + 3) * 384]);
;         float cv = x0 * w0 + x1 * w1 + x2 * w2 + x3 * w3;
;         val[t] = siluf_(cv);
;         x0 = x1; x1 = x2; x2 = x3;
;       }
.LBB0_804:
	s_or_b64 exec, exec, s[6:7]
	v_or_b32_e32 v0, s72, v135
	v_readlane_b32 s0, v254, 3
	v_lshlrev_b32_e32 v0, 2, v0
	v_mov_b32_e32 v1, v35
	v_readlane_b32 s4, v254, 7
	v_readlane_b32 s5, v254, 8
	s_waitcnt lgkmcnt(0)
	s_barrier
	v_lshl_add_u64 v[6:7], s[4:5], 0, v[0:1]
	v_add_co_u32_e32 v2, vcc, 0x1000, v6
	s_nop 1
	v_addc_co_u32_e32 v3, vcc, 0, v7, vcc
	v_add_co_u32_e32 v4, vcc, 0x3000, v6
	global_load_dword v0, v0, s[4:5]
	s_nop 0
	v_addc_co_u32_e32 v5, vcc, 0, v7, vcc
	global_load_dword v2, v[2:3], off offset:2048
	v_add_co_u32_e32 v6, vcc, 0x4000, v6
	global_load_dword v4, v[4:5], off
	s_nop 0
	v_addc_co_u32_e32 v7, vcc, 0, v7, vcc
	global_load_dword v6, v[6:7], off offset:2048
	ds_read_u16 v1, v193
	ds_read_u16 v3, v193 offset:768
	ds_read_u16 v5, v193 offset:1536
	ds_read_u16 v7, v193 offset:2304
	ds_read_u16 v47, v193 offset:3072
	ds_read_u16 v49, v193 offset:3840
	ds_read_u16 v51, v193 offset:4608
	ds_read_u16 v53, v193 offset:5376
	ds_read_u16 v98, v193 offset:6144
	ds_read_u16 v99, v193 offset:6912
	ds_read_u16 v100, v193 offset:7680
	ds_read_u16 v101, v193 offset:8448
	ds_read_u16 v102, v193 offset:9216
	ds_read_u16 v103, v193 offset:9984
	ds_read_u16 v104, v193 offset:10752
	ds_read_u16 v105, v193 offset:11520
	ds_read_u16 v106, v193 offset:12288
	ds_read_u16 v107, v193 offset:13056
	ds_read_u16 v108, v193 offset:13824
	ds_read_u16 v109, v193 offset:14592
	ds_read_u16 v110, v193 offset:15360
	ds_read_u16 v111, v193 offset:16128
	ds_read_u16 v112, v193 offset:16896
	ds_read_u16 v113, v193 offset:17664
	ds_read_u16 v114, v193 offset:18432
	ds_read_u16 v115, v193 offset:19200
	ds_read_u16 v116, v193 offset:19968
	ds_read_u16 v117, v193 offset:20736
	ds_read_u16 v82, v193 offset:21504
	ds_read_u16 v83, v193 offset:22272
	ds_read_u16 v84, v193 offset:23040
	ds_read_u16 v85, v193 offset:23808
	ds_read_u16 v54, v193 offset:24576
	ds_read_u16 v55, v193 offset:25344
	ds_read_u16 v56, v193 offset:26112
	ds_read_u16 v57, v193 offset:26880
	ds_read_u16 v58, v193 offset:27648
	ds_read_u16 v59, v193 offset:28416
	ds_read_u16 v60, v193 offset:29184
	ds_read_u16 v61, v193 offset:29952
	ds_read_u16 v30, v193 offset:30720
	ds_read_u16 v31, v193 offset:31488
	ds_read_u16 v28, v193 offset:32256
	ds_read_u16 v29, v193 offset:33024
	ds_read_u16 v26, v193 offset:33792
	ds_read_u16 v27, v193 offset:34560
	ds_read_u16 v86, v193 offset:35328
	ds_read_u16 v87, v193 offset:36096
	ds_read_u16 v66, v193 offset:36864
	ds_read_u16 v67, v193 offset:37632
	ds_read_u16 v64, v193 offset:38400
	ds_read_u16 v65, v193 offset:39168
	ds_read_u16 v62, v193 offset:39936
	ds_read_u16 v63, v193 offset:40704
	ds_read_u16 v24, v193 offset:41472
	ds_read_u16 v25, v193 offset:42240
	ds_read_u16 v22, v193 offset:43008
	ds_read_u16 v23, v193 offset:43776
	ds_read_u16 v20, v193 offset:44544
	ds_read_u16 v21, v193 offset:45312
	ds_read_u16 v8, v193 offset:46080
	ds_read_u16 v9, v193 offset:46848
	ds_read_u16 v10, v193 offset:47616
	ds_read_u16 v11, v193 offset:48384
	ds_read_u16 v16, v193 offset:49152
	ds_read_u16 v18, v193 offset:49920
	ds_read_u16 v19, v193 offset:50688
	s_waitcnt lgkmcnt(5)
	v_lshlrev_b32_e32 v13, 16, v9
	s_waitcnt lgkmcnt(4)
	v_lshlrev_b32_e32 v14, 16, v10
	v_lshlrev_b32_e32 v12, 16, v8
	v_mov_b32_e32 v8, v13
	v_mov_b32_e32 v9, v14
	s_waitcnt lgkmcnt(3)
	v_lshlrev_b32_e32 v15, 16, v11
	s_waitcnt lgkmcnt(2)
	v_lshlrev_b32_e32 v11, 16, v16
	v_mov_b32_e32 v10, v15
	v_lshlrev_b32_e32 v89, 16, v27
	v_lshlrev_b32_e32 v88, 16, v26
	v_lshlrev_b32_e32 v107, 16, v107
	v_lshlrev_b32_e32 v106, 16, v106
	v_lshlrev_b32_e32 v105, 16, v105
	v_lshlrev_b32_e32 v104, 16, v104
	v_lshlrev_b32_e32 v103, 16, v103
	v_lshlrev_b32_e32 v102, 16, v102
	v_readlane_b32 s1, v254, 4
	v_readlane_b32 s2, v254, 5
	v_readlane_b32 s3, v254, 6
	v_readlane_b32 s6, v254, 9
	v_readlane_b32 s7, v254, 10
	v_readlane_b32 s8, v254, 11
	v_readlane_b32 s9, v254, 12
	v_readlane_b32 s10, v254, 13
	v_readlane_b32 s11, v254, 14
	v_readlane_b32 s12, v254, 15
	v_readlane_b32 s13, v254, 16
	v_readlane_b32 s14, v254, 17
	v_readlane_b32 s15, v254, 18
	s_waitcnt vmcnt(2)
	v_pk_mul_f32 v[8:9], v[2:3], v[8:9] op_sel_hi:[0,1]
	v_pk_fma_f32 v[8:9], v[0:1], v[12:13], v[8:9] op_sel_hi:[0,1,1]
	s_waitcnt vmcnt(1)
	v_pk_fma_f32 v[8:9], v[4:5], v[14:15], v[8:9] op_sel_hi:[0,1,1]
	s_waitcnt vmcnt(0)
	v_pk_fma_f32 v[8:9], v[6:7], v[10:11], v[8:9] op_sel_hi:[0,1,1]
	v_mul_f32_e32 v16, 0xbfb8aa3b, v8
	v_mul_f32_e32 v17, 0xbfb8aa3b, v9
	v_exp_f32_e32 v16, v16
	v_exp_f32_e32 v17, v17
	v_add_f32_e32 v16, 1.0, v16
	v_add_f32_e32 v17, 1.0, v17
	v_rcp_f32_e32 v16, v16
	v_rcp_f32_e32 v17, v17
	s_nop 0
	v_pk_mul_f32 v[8:9], v[8:9], v[16:17]
	s_waitcnt lgkmcnt(1)
	v_lshlrev_b32_e32 v16, 16, v18
	s_waitcnt lgkmcnt(0)
; __device__ __forceinline__ float bf2f(u16 h) { return __uint_as_float(((unsigned)h) << 16); }
; __device__ __forceinline__ float siluf_(float x) { return x * __builtin_amdgcn_rcpf(1.f + __expf(-x)); }
; __device__ __forceinline__ void gdn_chunk_item(const Params& p, int item, char* smem) {
;     ...
;       for (int t = 0; t < 64; t++) {
;         float x3 = bf2f(tp[(t + 3) * 384]);
;         float cv = x0 * w0 + x1 * w1 + x2 * w2 + x3 * w3;
;         val[t] = siluf_(cv);
;         x0 = x1; x1 = x2; x2 = x3;
;       }
;     }
;     float sq[64];
; #pragma unroll
;     for (int t = 0; t < 64; t++) sq[t] = val[t] * val[t];
	v_lshlrev_b32_e32 v17, 16, v19
	v_pk_mov_b32 v[18:19], v[10:11], v[16:17] op_sel:[1,0]
	v_pk_mul_f32 v[10:11], v[2:3], v[10:11] op_sel_hi:[0,1]
	v_pk_fma_f32 v[10:11], v[0:1], v[14:15], v[10:11] op_sel_hi:[0,1,1]
	v_pk_fma_f32 v[10:11], v[4:5], v[18:19], v[10:11] op_sel_hi:[0,1,1]
	v_pk_fma_f32 v[10:11], v[6:7], v[16:17], v[10:11] op_sel_hi:[0,1,1]
	v_mul_f32_e32 v16, 0xbfb8aa3b, v10
	v_mul_f32_e32 v17, 0xbfb8aa3b, v11
	v_exp_f32_e32 v16, v16
	v_exp_f32_e32 v17, v17
	v_pk_mul_f32 v[74:75], v[8:9], v[8:9]
	v_add_f32_e32 v16, 1.0, v16
	v_add_f32_e32 v17, 1.0, v17
	v_rcp_f32_e32 v16, v16
	v_rcp_f32_e32 v17, v17
	s_nop 0
	v_pk_mul_f32 v[10:11], v[10:11], v[16:17]
	v_lshlrev_b32_e32 v17, 16, v21
	v_lshlrev_b32_e32 v16, 16, v20
	v_pk_mov_b32 v[18:19], v[16:17], v[12:13] op_sel:[1,0]
	v_pk_mul_f32 v[80:81], v[10:11], v[10:11]
	v_pk_mul_f32 v[20:21], v[2:3], v[18:19] op_sel_hi:[0,1]
	v_pk_fma_f32 v[20:21], v[0:1], v[16:17], v[20:21] op_sel_hi:[0,1,1]
	v_pk_fma_f32 v[20:21], v[4:5], v[12:13], v[20:21] op_sel_hi:[0,1,1]
	v_pk_mov_b32 v[12:13], v[12:13], v[14:15] op_sel:[1,0]
	s_nop 0
	v_pk_fma_f32 v[12:13], v[6:7], v[12:13], v[20:21] op_sel_hi:[0,1,1]
	v_mul_f32_e32 v14, 0xbfb8aa3b, v12
	v_mul_f32_e32 v15, 0xbfb8aa3b, v13
	v_exp_f32_e32 v14, v14
	v_exp_f32_e32 v15, v15
	v_lshlrev_b32_e32 v21, 16, v23
	v_lshlrev_b32_e32 v20, 16, v22
	v_add_f32_e32 v14, 1.0, v14
	v_add_f32_e32 v15, 1.0, v15
	v_rcp_f32_e32 v14, v14
	v_rcp_f32_e32 v15, v15
	v_pk_mov_b32 v[22:23], v[20:21], v[16:17] op_sel:[1,0]
	v_pk_mul_f32 v[12:13], v[12:13], v[14:15]
	v_pk_mul_f32 v[14:15], v[2:3], v[22:23] op_sel_hi:[0,1]
	v_pk_fma_f32 v[14:15], v[0:1], v[20:21], v[14:15] op_sel_hi:[0,1,1]
	v_pk_fma_f32 v[14:15], v[4:5], v[16:17], v[14:15] op_sel_hi:[0,1,1]
	v_pk_fma_f32 v[14:15], v[6:7], v[18:19], v[14:15] op_sel_hi:[0,1,1]
	v_mul_f32_e32 v16, 0xbfb8aa3b, v14
	v_mul_f32_e32 v17, 0xbfb8aa3b, v15
	v_exp_f32_e32 v16, v16
	v_exp_f32_e32 v17, v17
	v_lshlrev_b32_e32 v19, 16, v25
	v_lshlrev_b32_e32 v18, 16, v24
	v_add_f32_e32 v16, 1.0, v16
	v_add_f32_e32 v17, 1.0, v17
	v_rcp_f32_e32 v16, v16
	v_rcp_f32_e32 v17, v17
	v_pk_mov_b32 v[24:25], v[18:19], v[20:21] op_sel:[1,0]
	v_pk_mul_f32 v[78:79], v[12:13], v[12:13]
	v_pk_mul_f32 v[14:15], v[14:15], v[16:17]
	v_pk_mul_f32 v[16:17], v[2:3], v[24:25] op_sel_hi:[0,1]
	v_pk_fma_f32 v[16:17], v[0:1], v[18:19], v[16:17] op_sel_hi:[0,1,1]
	v_pk_fma_f32 v[16:17], v[4:5], v[20:21], v[16:17] op_sel_hi:[0,1,1]
	v_pk_fma_f32 v[16:17], v[6:7], v[22:23], v[16:17] op_sel_hi:[0,1,1]
	v_mul_f32_e32 v20, 0xbfb8aa3b, v16
	v_mul_f32_e32 v21, 0xbfb8aa3b, v17
	v_exp_f32_e32 v20, v20
	v_exp_f32_e32 v21, v21
	v_pk_mul_f32 v[76:77], v[14:15], v[14:15]
	v_add_f32_e32 v20, 1.0, v20
	v_add_f32_e32 v21, 1.0, v21
	v_rcp_f32_e32 v20, v20
	v_rcp_f32_e32 v21, v21
	s_nop 0
	v_pk_mul_f32 v[16:17], v[16:17], v[20:21]
	v_lshlrev_b32_e32 v21, 16, v63
	v_lshlrev_b32_e32 v20, 16, v62
	v_pk_mov_b32 v[22:23], v[20:21], v[18:19] op_sel:[1,0]
	v_pk_mul_f32 v[96:97], v[16:17], v[16:17]
	v_pk_mul_f32 v[62:63], v[2:3], v[22:23] op_sel_hi:[0,1]
	v_pk_fma_f32 v[62:63], v[0:1], v[20:21], v[62:63] op_sel_hi:[0,1,1]
	v_pk_fma_f32 v[18:19], v[4:5], v[18:19], v[62:63] op_sel_hi:[0,1,1]
	v_pk_fma_f32 v[18:19], v[6:7], v[24:25], v[18:19] op_sel_hi:[0,1,1]
	v_mul_f32_e32 v24, 0xbfb8aa3b, v18
	v_mul_f32_e32 v25, 0xbfb8aa3b, v19
	v_exp_f32_e32 v24, v24
	v_exp_f32_e32 v25, v25
	v_add_f32_e32 v24, 1.0, v24
	v_add_f32_e32 v25, 1.0, v25
	v_rcp_f32_e32 v24, v24
	v_rcp_f32_e32 v25, v25
	s_nop 0
	v_pk_mul_f32 v[18:19], v[18:19], v[24:25]
	v_lshlrev_b32_e32 v25, 16, v65
	v_lshlrev_b32_e32 v24, 16, v64
	v_pk_mov_b32 v[62:63], v[24:25], v[20:21] op_sel:[1,0]
	v_pk_mul_f32 v[72:73], v[18:19], v[18:19]
	v_pk_mul_f32 v[64:65], v[2:3], v[62:63] op_sel_hi:[0,1]
	v_pk_fma_f32 v[64:65], v[0:1], v[24:25], v[64:65] op_sel_hi:[0,1,1]
	v_pk_fma_f32 v[20:21], v[4:5], v[20:21], v[64:65] op_sel_hi:[0,1,1]
	v_pk_fma_f32 v[20:21], v[6:7], v[22:23], v[20:21] op_sel_hi:[0,1,1]
	v_mul_f32_e32 v22, 0xbfb8aa3b, v20
	v_mul_f32_e32 v23, 0xbfb8aa3b, v21
	v_exp_f32_e32 v22, v22
	v_exp_f32_e32 v23, v23
	v_lshlrev_b32_e32 v65, 16, v67
	v_lshlrev_b32_e32 v64, 16, v66
	v_add_f32_e32 v22, 1.0, v22
	v_add_f32_e32 v23, 1.0, v23
	v_rcp_f32_e32 v22, v22
	v_rcp_f32_e32 v23, v23
	v_pk_mov_b32 v[66:67], v[64:65], v[24:25] op_sel:[1,0]
	v_pk_mul_f32 v[20:21], v[20:21], v[22:23]
	v_pk_mul_f32 v[22:23], v[2:3], v[66:67] op_sel_hi:[0,1]
	v_pk_fma_f32 v[22:23], v[0:1], v[64:65], v[22:23] op_sel_hi:[0,1,1]
	v_pk_fma_f32 v[22:23], v[4:5], v[24:25], v[22:23] op_sel_hi:[0,1,1]
	v_pk_fma_f32 v[22:23], v[6:7], v[62:63], v[22:23] op_sel_hi:[0,1,1]
	v_mul_f32_e32 v24, 0xbfb8aa3b, v22
	v_mul_f32_e32 v25, 0xbfb8aa3b, v23
	v_exp_f32_e32 v24, v24
	v_exp_f32_e32 v25, v25
	v_lshlrev_b32_e32 v63, 16, v87
	v_lshlrev_b32_e32 v62, 16, v86
	v_add_f32_e32 v24, 1.0, v24
	v_add_f32_e32 v25, 1.0, v25
	v_rcp_f32_e32 v24, v24
	v_rcp_f32_e32 v25, v25
	v_pk_mov_b32 v[90:91], v[88:89], v[62:63] op_sel:[1,0]
	v_pk_mov_b32 v[86:87], v[62:63], v[64:65] op_sel:[1,0]
	v_pk_mul_f32 v[26:27], v[2:3], v[90:91] op_sel_hi:[0,1]
	v_pk_fma_f32 v[26:27], v[0:1], v[88:89], v[26:27] op_sel_hi:[0,1,1]
	v_pk_fma_f32 v[26:27], v[4:5], v[62:63], v[26:27] op_sel_hi:[0,1,1]
	v_pk_mul_f32 v[22:23], v[22:23], v[24:25]
	v_pk_mul_f32 v[24:25], v[2:3], v[86:87] op_sel_hi:[0,1]
	v_pk_fma_f32 v[26:27], v[6:7], v[86:87], v[26:27] op_sel_hi:[0,1,1]
	v_lshlrev_b32_e32 v87, 16, v29
	v_lshlrev_b32_e32 v86, 16, v28
	v_pk_mov_b32 v[92:93], v[86:87], v[88:89] op_sel:[1,0]
	v_pk_mul_f32 v[70:71], v[20:21], v[20:21]
	v_pk_mul_f32 v[28:29], v[2:3], v[92:93] op_sel_hi:[0,1]
	v_pk_fma_f32 v[28:29], v[0:1], v[86:87], v[28:29] op_sel_hi:[0,1,1]
; __device__ __forceinline__ float bf2f(u16 h) { return __uint_as_float(((unsigned)h) << 16); }
; __device__ __forceinline__ float siluf_(float x) { return x * __builtin_amdgcn_rcpf(1.f + __expf(-x)); }
; __device__ __forceinline__ float transpose_reduce64(float (&v)[64], int lane) {
; #pragma unroll
;   for (int i = 0; i < 32; i++) { bool hi = lane & 32; float send = hi ? v[i] : v[i + 32]; float keep = hi ? v[i + 32] : v[i]; v[i] = keep + __shfl_xor(send, 32); }
; __device__ __forceinline__ void gdn_chunk_item(const Params& p, int item, char* smem) {
;     ...
;       for (int t = 0; t < 64; t++) {
;         float x3 = bf2f(tp[(t + 3) * 384]);
;         float cv = x0 * w0 + x1 * w1 + x2 * w2 + x3 * w3;
;         val[t] = siluf_(cv);
;         x0 = x1; x1 = x2; x2 = x3;
;       }
;     }
;     float sq[64];
; #pragma unroll
;     for (int t = 0; t < 64; t++) sq[t] = val[t] * val[t];
;     float part = transpose_reduce64(sq, lane);
	v_pk_fma_f32 v[28:29], v[4:5], v[88:89], v[28:29] op_sel_hi:[0,1,1]
	v_lshlrev_b32_e32 v89, 16, v31
	v_lshlrev_b32_e32 v88, 16, v30
	v_pk_fma_f32 v[28:29], v[6:7], v[90:91], v[28:29] op_sel_hi:[0,1,1]
	v_pk_mov_b32 v[90:91], v[88:89], v[86:87] op_sel:[1,0]
	v_pk_mul_f32 v[68:69], v[22:23], v[22:23]
	v_pk_mul_f32 v[30:31], v[2:3], v[90:91] op_sel_hi:[0,1]
	v_pk_fma_f32 v[30:31], v[0:1], v[88:89], v[30:31] op_sel_hi:[0,1,1]
	v_pk_fma_f32 v[30:31], v[4:5], v[86:87], v[30:31] op_sel_hi:[0,1,1]
	v_pk_fma_f32 v[30:31], v[6:7], v[92:93], v[30:31] op_sel_hi:[0,1,1]
	v_mul_f32_e32 v86, 0xbfb8aa3b, v30
	v_mul_f32_e32 v87, 0xbfb8aa3b, v31
	v_exp_f32_e32 v86, v86
	v_exp_f32_e32 v87, v87
	v_pk_fma_f32 v[24:25], v[0:1], v[62:63], v[24:25] op_sel_hi:[0,1,1]
	v_pk_fma_f32 v[24:25], v[4:5], v[64:65], v[24:25] op_sel_hi:[0,1,1]
	v_add_f32_e32 v86, 1.0, v86
	v_add_f32_e32 v87, 1.0, v87
	v_rcp_f32_e32 v86, v86
	v_rcp_f32_e32 v87, v87
	v_pk_fma_f32 v[24:25], v[6:7], v[66:67], v[24:25] op_sel_hi:[0,1,1]
	v_mul_f32_e32 v64, 0xbfb8aa3b, v24
	v_mul_f32_e32 v65, 0xbfb8aa3b, v25
	v_pk_mul_f32 v[30:31], v[30:31], v[86:87]
	v_lshlrev_b32_e32 v87, 16, v61
	v_lshlrev_b32_e32 v86, 16, v60
	v_pk_mov_b32 v[118:119], v[86:87], v[88:89] op_sel:[1,0]
	v_exp_f32_e32 v64, v64
	v_pk_mul_f32 v[60:61], v[2:3], v[118:119] op_sel_hi:[0,1]
	v_pk_fma_f32 v[60:61], v[0:1], v[86:87], v[60:61] op_sel_hi:[0,1,1]
	v_pk_fma_f32 v[60:61], v[4:5], v[88:89], v[60:61] op_sel_hi:[0,1,1]
	v_pk_fma_f32 v[60:61], v[6:7], v[90:91], v[60:61] op_sel_hi:[0,1,1]
	v_mul_f32_e32 v88, 0xbfb8aa3b, v60
	v_mul_f32_e32 v89, 0xbfb8aa3b, v61
	v_exp_f32_e32 v88, v88
	v_exp_f32_e32 v89, v89
	v_exp_f32_e32 v65, v65
	v_add_f32_e32 v64, 1.0, v64
	v_add_f32_e32 v88, 1.0, v88
	v_add_f32_e32 v89, 1.0, v89
	v_rcp_f32_e32 v88, v88
	v_rcp_f32_e32 v89, v89
	v_add_f32_e32 v65, 1.0, v65
	v_rcp_f32_e32 v64, v64
	v_rcp_f32_e32 v65, v65
	v_pk_mul_f32 v[92:93], v[60:61], v[88:89]
	v_lshlrev_b32_e32 v89, 16, v59
	v_lshlrev_b32_e32 v88, 16, v58
	v_pk_mov_b32 v[120:121], v[88:89], v[86:87] op_sel:[1,0]
	v_pk_mul_f32 v[24:25], v[24:25], v[64:65]
	v_pk_mul_f32 v[58:59], v[2:3], v[120:121] op_sel_hi:[0,1]
	v_pk_fma_f32 v[58:59], v[0:1], v[88:89], v[58:59] op_sel_hi:[0,1,1]
	v_pk_fma_f32 v[58:59], v[4:5], v[86:87], v[58:59] op_sel_hi:[0,1,1]
	v_pk_fma_f32 v[58:59], v[6:7], v[118:119], v[58:59] op_sel_hi:[0,1,1]
	v_mul_f32_e32 v86, 0xbfb8aa3b, v58
	v_mul_f32_e32 v87, 0xbfb8aa3b, v59
	v_exp_f32_e32 v86, v86
	v_exp_f32_e32 v87, v87
	v_pk_mul_f32 v[66:67], v[24:25], v[24:25]
	v_mul_f32_e32 v62, 0xbfb8aa3b, v26
	v_add_f32_e32 v86, 1.0, v86
	v_add_f32_e32 v87, 1.0, v87
	v_rcp_f32_e32 v86, v86
	v_rcp_f32_e32 v87, v87
	v_mul_f32_e32 v63, 0xbfb8aa3b, v27
	v_exp_f32_e32 v62, v62
	v_exp_f32_e32 v63, v63
	v_pk_mul_f32 v[90:91], v[58:59], v[86:87]
	v_lshlrev_b32_e32 v87, 16, v57
	v_lshlrev_b32_e32 v86, 16, v56
	v_pk_mov_b32 v[118:119], v[86:87], v[88:89] op_sel:[1,0]
	v_add_f32_e32 v62, 1.0, v62
	v_pk_mul_f32 v[56:57], v[2:3], v[118:119] op_sel_hi:[0,1]
	v_pk_fma_f32 v[56:57], v[0:1], v[86:87], v[56:57] op_sel_hi:[0,1,1]
	v_pk_fma_f32 v[56:57], v[4:5], v[88:89], v[56:57] op_sel_hi:[0,1,1]
	v_pk_fma_f32 v[56:57], v[6:7], v[120:121], v[56:57] op_sel_hi:[0,1,1]
	v_lshlrev_b32_e32 v121, 16, v55
	v_lshlrev_b32_e32 v120, 16, v54
	v_pk_mov_b32 v[122:123], v[120:121], v[86:87] op_sel:[1,0]
	v_add_f32_e32 v63, 1.0, v63
	v_pk_mul_f32 v[54:55], v[2:3], v[122:123] op_sel_hi:[0,1]
	v_pk_fma_f32 v[54:55], v[0:1], v[120:121], v[54:55] op_sel_hi:[0,1,1]
	v_pk_fma_f32 v[54:55], v[4:5], v[86:87], v[54:55] op_sel_hi:[0,1,1]
	v_pk_fma_f32 v[54:55], v[6:7], v[118:119], v[54:55] op_sel_hi:[0,1,1]
	v_lshlrev_b32_e32 v119, 16, v85
	v_lshlrev_b32_e32 v118, 16, v84
	v_pk_mov_b32 v[124:125], v[118:119], v[120:121] op_sel:[1,0]
	v_rcp_f32_e32 v62, v62
	v_pk_mul_f32 v[84:85], v[2:3], v[124:125] op_sel_hi:[0,1]
	v_pk_fma_f32 v[84:85], v[0:1], v[118:119], v[84:85] op_sel_hi:[0,1,1]
	v_pk_fma_f32 v[84:85], v[4:5], v[120:121], v[84:85] op_sel_hi:[0,1,1]
	v_pk_fma_f32 v[84:85], v[6:7], v[122:123], v[84:85] op_sel_hi:[0,1,1]
	v_mul_f32_e32 v120, 0xbfb8aa3b, v84
	v_mul_f32_e32 v121, 0xbfb8aa3b, v85
	v_exp_f32_e32 v120, v120
	v_exp_f32_e32 v121, v121
	v_rcp_f32_e32 v63, v63
	v_pk_mul_f32 v[94:95], v[30:31], v[30:31]
	v_add_f32_e32 v120, 1.0, v120
	v_add_f32_e32 v121, 1.0, v121
	v_rcp_f32_e32 v120, v120
	v_rcp_f32_e32 v121, v121
	v_pk_mul_f32 v[26:27], v[26:27], v[62:63]
	v_mul_f32_e32 v62, 0xbfb8aa3b, v28
	v_pk_mul_f32 v[64:65], v[26:27], v[26:27]
	v_pk_mul_f32 v[84:85], v[84:85], v[120:121]
	v_mul_f32_e32 v63, 0xbfb8aa3b, v29
	v_pk_mul_f32 v[122:123], v[84:85], v[84:85]
	v_exp_f32_e32 v62, v62
	v_cndmask_b32_e64 v120, v122, v80, s[18:19]
	s_nop 1
	v_permlane32_swap_b32_e32 v120, v120
	v_cndmask_b32_e64 v80, v80, v122, s[18:19]
	v_exp_f32_e32 v63, v63
	v_add_f32_e32 v62, 1.0, v62
	v_rcp_f32_e32 v62, v62
	s_waitcnt lgkmcnt(0)
	v_add_f32_e32 v121, v80, v120
	v_cndmask_b32_e64 v80, v123, v81, s[18:19]
	s_nop 1
	v_permlane32_swap_b32_e32 v80, v80
	v_cndmask_b32_e64 v81, v81, v123, s[18:19]
	v_add_f32_e32 v63, 1.0, v63
	v_rcp_f32_e32 v63, v63
	v_pk_mul_f32 v[60:61], v[92:93], v[92:93]
	s_waitcnt lgkmcnt(0)
; __device__ __forceinline__ float bf2f(u16 h) { return __uint_as_float(((unsigned)h) << 16); }
; __device__ __forceinline__ float siluf_(float x) { return x * __builtin_amdgcn_rcpf(1.f + __expf(-x)); }
; __device__ __forceinline__ float transpose_reduce64(float (&v)[64], int lane) {
; #pragma unroll
;   for (int i = 0; i < 32; i++) { bool hi = lane & 32; float send = hi ? v[i] : v[i + 32]; float keep = hi ? v[i + 32] : v[i]; v[i] = keep + __shfl_xor(send, 32); }
; __device__ __forceinline__ void gdn_chunk_item(const Params& p, int item, char* smem) {
;     ...
;       for (int t = 0; t < 64; t++) {
;         float x3 = bf2f(tp[(t + 3) * 384]);
;         float cv = x0 * w0 + x1 * w1 + x2 * w2 + x3 * w3;
;         val[t] = siluf_(cv);
;         x0 = x1; x1 = x2; x2 = x3;
;       }
;     }
;     float sq[64];
; #pragma unroll
;     for (int t = 0; t < 64; t++) sq[t] = val[t] * val[t];
;     float part = transpose_reduce64(sq, lane);
	v_add_f32_e32 v120, v81, v80
	v_lshlrev_b32_e32 v81, 16, v83
	v_lshlrev_b32_e32 v80, 16, v82
	v_pk_mov_b32 v[122:123], v[80:81], v[118:119] op_sel:[1,0]
	v_pk_mul_f32 v[28:29], v[28:29], v[62:63]
	v_pk_mul_f32 v[82:83], v[2:3], v[122:123] op_sel_hi:[0,1]
	v_pk_fma_f32 v[82:83], v[0:1], v[80:81], v[82:83] op_sel_hi:[0,1,1]
	v_pk_fma_f32 v[82:83], v[4:5], v[118:119], v[82:83] op_sel_hi:[0,1,1]
	v_pk_fma_f32 v[82:83], v[6:7], v[124:125], v[82:83] op_sel_hi:[0,1,1]
	v_mul_f32_e32 v118, 0xbfb8aa3b, v82
	v_mul_f32_e32 v119, 0xbfb8aa3b, v83
	v_exp_f32_e32 v118, v118
	v_exp_f32_e32 v119, v119
	v_pk_mul_f32 v[62:63], v[28:29], v[28:29]
	v_pk_mul_f32 v[58:59], v[90:91], v[90:91]
	v_add_f32_e32 v118, 1.0, v118
	v_add_f32_e32 v119, 1.0, v119
	v_rcp_f32_e32 v118, v118
	v_rcp_f32_e32 v119, v119
	v_mul_f32_e32 v88, 0xbfb8aa3b, v56
	v_mul_f32_e32 v89, 0xbfb8aa3b, v57
	v_exp_f32_e32 v88, v88
	v_pk_mul_f32 v[82:83], v[82:83], v[118:119]
	v_exp_f32_e32 v89, v89
	v_pk_mul_f32 v[124:125], v[82:83], v[82:83]
	v_add_f32_e32 v88, 1.0, v88
	v_cndmask_b32_e64 v118, v124, v74, s[18:19]
	s_nop 1
	v_permlane32_swap_b32_e32 v118, v118
	v_cndmask_b32_e64 v74, v74, v124, s[18:19]
	v_add_f32_e32 v89, 1.0, v89
	v_rcp_f32_e32 v88, v88
	v_rcp_f32_e32 v89, v89
	s_waitcnt lgkmcnt(0)
	v_add_f32_e32 v119, v74, v118
	v_cndmask_b32_e64 v74, v125, v75, s[18:19]
	s_nop 1
	v_permlane32_swap_b32_e32 v74, v74
	v_cndmask_b32_e64 v75, v75, v125, s[18:19]
	v_pk_mul_f32 v[88:89], v[56:57], v[88:89]
	v_mul_f32_e32 v86, 0xbfb8aa3b, v54
	v_pk_mul_f32 v[56:57], v[88:89], v[88:89]
	s_waitcnt lgkmcnt(0)
	v_add_f32_e32 v118, v75, v74
	v_lshlrev_b32_e32 v75, 16, v117
	v_lshlrev_b32_e32 v74, 16, v116
	v_pk_mov_b32 v[124:125], v[74:75], v[80:81] op_sel:[1,0]
	v_mul_f32_e32 v87, 0xbfb8aa3b, v55
	v_pk_mul_f32 v[116:117], v[2:3], v[124:125] op_sel_hi:[0,1]
	v_pk_fma_f32 v[116:117], v[0:1], v[74:75], v[116:117] op_sel_hi:[0,1,1]
	v_pk_fma_f32 v[80:81], v[4:5], v[80:81], v[116:117] op_sel_hi:[0,1,1]
	v_pk_fma_f32 v[80:81], v[6:7], v[122:123], v[80:81] op_sel_hi:[0,1,1]
	v_mul_f32_e32 v116, 0xbfb8aa3b, v80
	v_mul_f32_e32 v117, 0xbfb8aa3b, v81
	v_exp_f32_e32 v116, v116
	v_exp_f32_e32 v117, v117
	v_exp_f32_e32 v86, v86
	v_exp_f32_e32 v87, v87
	v_add_f32_e32 v116, 1.0, v116
	v_add_f32_e32 v117, 1.0, v117
	v_rcp_f32_e32 v116, v116
	v_rcp_f32_e32 v117, v117
	v_add_f32_e32 v86, 1.0, v86
	v_add_f32_e32 v87, 1.0, v87
	v_rcp_f32_e32 v86, v86
	v_pk_mul_f32 v[80:81], v[80:81], v[116:117]
	v_rcp_f32_e32 v87, v87
	v_pk_mul_f32 v[122:123], v[80:81], v[80:81]
	v_pk_mul_f32 v[86:87], v[54:55], v[86:87]
	v_cndmask_b32_e64 v116, v122, v78, s[18:19]
	s_nop 1
	v_permlane32_swap_b32_e32 v116, v116
	v_cndmask_b32_e64 v78, v78, v122, s[18:19]
	v_lshlrev_b32_e32 v122, 16, v114
	v_pk_mul_f32 v[54:55], v[86:87], v[86:87]
	s_waitcnt lgkmcnt(0)
	v_add_f32_e32 v117, v78, v116
	v_cndmask_b32_e64 v78, v123, v79, s[18:19]
	s_nop 1
	v_permlane32_swap_b32_e32 v78, v78
	v_cndmask_b32_e64 v79, v79, v123, s[18:19]
	v_lshlrev_b32_e32 v123, 16, v115
	v_pk_mov_b32 v[126:127], v[122:123], v[74:75] op_sel:[1,0]
	s_waitcnt lgkmcnt(0)
	v_add_f32_e32 v116, v79, v78
	v_pk_mul_f32 v[78:79], v[2:3], v[126:127] op_sel_hi:[0,1]
	v_pk_fma_f32 v[78:79], v[0:1], v[122:123], v[78:79] op_sel_hi:[0,1,1]
	v_pk_fma_f32 v[74:75], v[4:5], v[74:75], v[78:79] op_sel_hi:[0,1,1]
	v_pk_fma_f32 v[74:75], v[6:7], v[124:125], v[74:75] op_sel_hi:[0,1,1]
	v_mul_f32_e32 v78, 0xbfb8aa3b, v74
	v_mul_f32_e32 v79, 0xbfb8aa3b, v75
	v_exp_f32_e32 v78, v78
	v_exp_f32_e32 v79, v79
	v_add_f32_e32 v78, 1.0, v78
	v_add_f32_e32 v79, 1.0, v79
	v_rcp_f32_e32 v78, v78
	v_rcp_f32_e32 v79, v79
	s_nop 0
	v_pk_mul_f32 v[78:79], v[74:75], v[78:79]
	s_nop 0
	v_pk_mul_f32 v[74:75], v[78:79], v[78:79]
	s_nop 0
	v_cndmask_b32_e64 v114, v74, v76, s[18:19]
	v_cndmask_b32_e64 v74, v76, v74, s[18:19]
	v_mov_b32_e32 v76, v114
	s_nop 1
	v_permlane32_swap_b32_e32 v76, v76
	s_waitcnt lgkmcnt(0)
	v_add_f32_e32 v115, v74, v76
	v_cndmask_b32_e64 v74, v75, v77, s[18:19]
	s_nop 1
	v_permlane32_swap_b32_e32 v74, v74
	v_cndmask_b32_e64 v75, v77, v75, s[18:19]
	s_waitcnt lgkmcnt(0)
	v_add_f32_e32 v114, v75, v74
	v_lshlrev_b32_e32 v75, 16, v113
	v_lshlrev_b32_e32 v74, 16, v112
	v_pk_mov_b32 v[124:125], v[74:75], v[122:123] op_sel:[1,0]
	s_nop 0
	v_pk_mul_f32 v[76:77], v[2:3], v[124:125] op_sel_hi:[0,1]
	v_pk_fma_f32 v[76:77], v[0:1], v[74:75], v[76:77] op_sel_hi:[0,1,1]
	v_pk_fma_f32 v[76:77], v[4:5], v[122:123], v[76:77] op_sel_hi:[0,1,1]
	v_pk_fma_f32 v[76:77], v[6:7], v[126:127], v[76:77] op_sel_hi:[0,1,1]
	v_mul_f32_e32 v112, 0xbfb8aa3b, v76
	v_mul_f32_e32 v113, 0xbfb8aa3b, v77
	v_exp_f32_e32 v112, v112
	v_exp_f32_e32 v113, v113
	v_add_f32_e32 v112, 1.0, v112
	v_add_f32_e32 v113, 1.0, v113
	v_rcp_f32_e32 v112, v112
	v_rcp_f32_e32 v113, v113
	s_nop 0
	v_pk_mul_f32 v[76:77], v[76:77], v[112:113]
	s_nop 0
	v_pk_mul_f32 v[122:123], v[76:77], v[76:77]
	s_nop 0
	v_cndmask_b32_e64 v112, v122, v96, s[18:19]
	s_nop 1
	v_permlane32_swap_b32_e32 v112, v112
	v_cndmask_b32_e64 v96, v96, v122, s[18:19]
	s_waitcnt lgkmcnt(0)
	v_add_f32_e32 v113, v96, v112
	v_cndmask_b32_e64 v96, v123, v97, s[18:19]
	s_nop 1
	v_permlane32_swap_b32_e32 v96, v96
	v_cndmask_b32_e64 v97, v97, v123, s[18:19]
	s_waitcnt lgkmcnt(0)
; __device__ __forceinline__ float bf2f(u16 h) { return __uint_as_float(((unsigned)h) << 16); }
; __device__ __forceinline__ float siluf_(float x) { return x * __builtin_amdgcn_rcpf(1.f + __expf(-x)); }
; __device__ __forceinline__ float transpose_reduce64(float (&v)[64], int lane) {
; #pragma unroll
;   for (int i = 0; i < 32; i++) { bool hi = lane & 32; float send = hi ? v[i] : v[i + 32]; float keep = hi ? v[i + 32] : v[i]; v[i] = keep + __shfl_xor(send, 32); }
; #pragma unroll
;   for (int i = 0; i < 16; i++) { bool hi = lane & 16; float send = hi ? v[i] : v[i + 16]; float keep = hi ? v[i + 16] : v[i]; v[i] = keep + __shfl_xor(send, 16); }
; __device__ __forceinline__ void gdn_chunk_item(const Params& p, int item, char* smem) {
;     ...
;       for (int t = 0; t < 64; t++) {
;         float x3 = bf2f(tp[(t + 3) * 384]);
;         float cv = x0 * w0 + x1 * w1 + x2 * w2 + x3 * w3;
;         val[t] = siluf_(cv);
;         x0 = x1; x1 = x2; x2 = x3;
;       }
;     }
;     float sq[64];
; #pragma unroll
;     for (int t = 0; t < 64; t++) sq[t] = val[t] * val[t];
;     float part = transpose_reduce64(sq, lane);
	v_add_f32_e32 v112, v97, v96
	v_lshlrev_b32_e32 v97, 16, v111
	v_lshlrev_b32_e32 v96, 16, v110
	v_pk_mov_b32 v[122:123], v[96:97], v[74:75] op_sel:[1,0]
	s_nop 0
	v_pk_mul_f32 v[110:111], v[2:3], v[122:123] op_sel_hi:[0,1]
	v_pk_fma_f32 v[110:111], v[0:1], v[96:97], v[110:111] op_sel_hi:[0,1,1]
	v_pk_fma_f32 v[74:75], v[4:5], v[74:75], v[110:111] op_sel_hi:[0,1,1]
	v_pk_fma_f32 v[74:75], v[6:7], v[124:125], v[74:75] op_sel_hi:[0,1,1]
	v_mul_f32_e32 v110, 0xbfb8aa3b, v74
	v_mul_f32_e32 v111, 0xbfb8aa3b, v75
	v_exp_f32_e32 v110, v110
	v_exp_f32_e32 v111, v111
	v_add_f32_e32 v110, 1.0, v110
	v_add_f32_e32 v111, 1.0, v111
	v_rcp_f32_e32 v110, v110
	v_rcp_f32_e32 v111, v111
	s_nop 0
	v_pk_mul_f32 v[74:75], v[74:75], v[110:111]
	s_nop 0
	v_pk_mul_f32 v[124:125], v[74:75], v[74:75]
	s_nop 0
	v_cndmask_b32_e64 v110, v124, v72, s[18:19]
	s_nop 1
	v_permlane32_swap_b32_e32 v110, v110
	v_cndmask_b32_e64 v72, v72, v124, s[18:19]
	v_lshlrev_b32_e32 v124, 16, v108
	s_waitcnt lgkmcnt(0)
	v_add_f32_e32 v111, v72, v110
	v_cndmask_b32_e64 v72, v125, v73, s[18:19]
	s_nop 1
	v_permlane32_swap_b32_e32 v72, v72
	v_cndmask_b32_e64 v73, v73, v125, s[18:19]
	v_lshlrev_b32_e32 v125, 16, v109
	v_pk_mov_b32 v[126:127], v[124:125], v[96:97] op_sel:[1,0]
	s_waitcnt lgkmcnt(0)
	v_add_f32_e32 v110, v73, v72
	v_pk_mul_f32 v[72:73], v[2:3], v[126:127] op_sel_hi:[0,1]
	v_pk_fma_f32 v[72:73], v[0:1], v[124:125], v[72:73] op_sel_hi:[0,1,1]
	v_pk_fma_f32 v[72:73], v[4:5], v[96:97], v[72:73] op_sel_hi:[0,1,1]
	v_pk_fma_f32 v[72:73], v[6:7], v[122:123], v[72:73] op_sel_hi:[0,1,1]
	v_mul_f32_e32 v96, 0xbfb8aa3b, v72
	v_mul_f32_e32 v97, 0xbfb8aa3b, v73
	v_exp_f32_e32 v96, v96
	v_exp_f32_e32 v97, v97
	v_pk_mov_b32 v[122:123], v[106:107], v[124:125] op_sel:[1,0]
	v_add_f32_e32 v96, 1.0, v96
	v_add_f32_e32 v97, 1.0, v97
	v_rcp_f32_e32 v96, v96
	v_rcp_f32_e32 v97, v97
	s_nop 0
	v_pk_mul_f32 v[72:73], v[72:73], v[96:97]
	s_nop 0
	v_pk_mul_f32 v[96:97], v[72:73], v[72:73]
	s_nop 0
	v_cndmask_b32_e64 v108, v96, v70, s[18:19]
	v_cndmask_b32_e64 v70, v70, v96, s[18:19]
	v_mov_b32_e32 v96, v108
	s_nop 1
	v_permlane32_swap_b32_e32 v96, v96
	s_waitcnt lgkmcnt(0)
	v_add_f32_e32 v109, v70, v96
	v_cndmask_b32_e64 v70, v97, v71, s[18:19]
	s_nop 1
	v_permlane32_swap_b32_e32 v70, v70
	v_cndmask_b32_e64 v71, v71, v97, s[18:19]
	s_waitcnt lgkmcnt(0)
	v_add_f32_e32 v108, v71, v70
	v_pk_mul_f32 v[70:71], v[2:3], v[122:123] op_sel_hi:[0,1]
	v_pk_fma_f32 v[70:71], v[0:1], v[106:107], v[70:71] op_sel_hi:[0,1,1]
	v_pk_fma_f32 v[70:71], v[4:5], v[124:125], v[70:71] op_sel_hi:[0,1,1]
	v_pk_fma_f32 v[70:71], v[6:7], v[126:127], v[70:71] op_sel_hi:[0,1,1]
	v_mul_f32_e32 v96, 0xbfb8aa3b, v70
	v_mul_f32_e32 v97, 0xbfb8aa3b, v71
	v_exp_f32_e32 v96, v96
	v_exp_f32_e32 v97, v97
	v_add_f32_e32 v96, 1.0, v96
	v_add_f32_e32 v97, 1.0, v97
	v_rcp_f32_e32 v96, v96
	v_rcp_f32_e32 v97, v97
	s_nop 0
	v_pk_mul_f32 v[70:71], v[70:71], v[96:97]
	s_nop 0
	v_pk_mul_f32 v[124:125], v[70:71], v[70:71]
	s_nop 0
	v_cndmask_b32_e64 v96, v124, v68, s[18:19]
	s_nop 1
	v_permlane32_swap_b32_e32 v96, v96
	v_cndmask_b32_e64 v68, v68, v124, s[18:19]
	s_waitcnt lgkmcnt(0)
	v_add_f32_e32 v97, v68, v96
	v_cndmask_b32_e64 v68, v125, v69, s[18:19]
	s_nop 1
	v_permlane32_swap_b32_e32 v68, v68
	v_cndmask_b32_e64 v69, v69, v125, s[18:19]
	v_pk_mov_b32 v[124:125], v[104:105], v[106:107] op_sel:[1,0]
	s_waitcnt lgkmcnt(0)
	v_add_f32_e32 v96, v69, v68
	v_pk_mul_f32 v[68:69], v[2:3], v[124:125] op_sel_hi:[0,1]
	v_pk_fma_f32 v[68:69], v[0:1], v[104:105], v[68:69] op_sel_hi:[0,1,1]
	v_pk_fma_f32 v[68:69], v[4:5], v[106:107], v[68:69] op_sel_hi:[0,1,1]
	v_pk_fma_f32 v[68:69], v[6:7], v[122:123], v[68:69] op_sel_hi:[0,1,1]
	v_mul_f32_e32 v106, 0xbfb8aa3b, v68
	v_mul_f32_e32 v107, 0xbfb8aa3b, v69
	v_exp_f32_e32 v106, v106
	v_exp_f32_e32 v107, v107
	v_add_f32_e32 v106, 1.0, v106
	v_add_f32_e32 v107, 1.0, v107
	v_rcp_f32_e32 v106, v106
	v_rcp_f32_e32 v107, v107
	s_nop 0
	v_pk_mul_f32 v[68:69], v[68:69], v[106:107]
	s_nop 0
	v_pk_mul_f32 v[106:107], v[68:69], v[68:69]
	s_nop 0
	v_cndmask_b32_e64 v122, v106, v66, s[18:19]
	v_cndmask_b32_e64 v66, v66, v106, s[18:19]
	v_mov_b32_e32 v106, v122
	s_nop 1
	v_permlane32_swap_b32_e32 v106, v106
	s_waitcnt lgkmcnt(0)
	v_add_f32_e32 v66, v66, v106
	v_cndmask_b32_e64 v106, v66, v121, s[20:21]
	s_nop 1
	v_permlane16_swap_b32_e32 v106, v106
	v_cndmask_b32_e64 v66, v121, v66, s[20:21]
	s_waitcnt lgkmcnt(0)
	v_add_f32_e32 v121, v66, v106
	v_cndmask_b32_e64 v66, v107, v67, s[18:19]
	s_nop 1
	v_permlane32_swap_b32_e32 v66, v66
	v_cndmask_b32_e64 v67, v67, v107, s[18:19]
	v_pk_mov_b32 v[106:107], v[102:103], v[104:105] op_sel:[1,0]
	s_waitcnt lgkmcnt(0)
	v_add_f32_e32 v66, v67, v66
	v_cndmask_b32_e64 v67, v66, v120, s[20:21]
	s_nop 1
	v_permlane16_swap_b32_e32 v67, v67
	v_cndmask_b32_e64 v66, v120, v66, s[20:21]
	s_waitcnt lgkmcnt(0)
	v_add_f32_e32 v120, v66, v67
	v_pk_mul_f32 v[66:67], v[2:3], v[106:107] op_sel_hi:[0,1]
	v_pk_fma_f32 v[66:67], v[0:1], v[102:103], v[66:67] op_sel_hi:[0,1,1]
	v_pk_fma_f32 v[66:67], v[4:5], v[104:105], v[66:67] op_sel_hi:[0,1,1]
	v_pk_fma_f32 v[66:67], v[6:7], v[124:125], v[66:67] op_sel_hi:[0,1,1]
	v_mul_f32_e32 v104, 0xbfb8aa3b, v66
	v_mul_f32_e32 v105, 0xbfb8aa3b, v67
	v_exp_f32_e32 v104, v104
	v_exp_f32_e32 v105, v105
	v_add_f32_e32 v104, 1.0, v104
	v_add_f32_e32 v105, 1.0, v105
	v_rcp_f32_e32 v104, v104
	v_rcp_f32_e32 v105, v105
	s_nop 0
	v_pk_mul_f32 v[66:67], v[66:67], v[104:105]
	s_nop 0
	v_pk_mul_f32 v[104:105], v[66:67], v[66:67]
	s_nop 0
	v_cndmask_b32_e64 v122, v104, v64, s[18:19]
	v_cndmask_b32_e64 v64, v64, v104, s[18:19]
	v_mov_b32_e32 v104, v122
	s_nop 1
	v_permlane32_swap_b32_e32 v104, v104
	s_waitcnt lgkmcnt(0)
; __device__ __forceinline__ float bf2f(u16 h) { return __uint_as_float(((unsigned)h) << 16); }
; __device__ __forceinline__ float siluf_(float x) { return x * __builtin_amdgcn_rcpf(1.f + __expf(-x)); }
; __device__ __forceinline__ float transpose_reduce64(float (&v)[64], int lane) {
; #pragma unroll
;   for (int i = 0; i < 32; i++) { bool hi = lane & 32; float send = hi ? v[i] : v[i + 32]; float keep = hi ? v[i + 32] : v[i]; v[i] = keep + __shfl_xor(send, 32); }
; #pragma unroll
;   for (int i = 0; i < 16; i++) { bool hi = lane & 16; float send = hi ? v[i] : v[i + 16]; float keep = hi ? v[i + 16] : v[i]; v[i] = keep + __shfl_xor(send, 16); }
; #pragma unroll
;   for (int i = 0; i < 8; i++) { bool hi = lane & 8; float send = hi ? v[i] : v[i + 8]; float keep = hi ? v[i + 8] : v[i]; v[i] = keep + __shfl_xor(send, 8); }
; #pragma unroll
;   for (int i = 0; i < 4; i++) { bool hi = lane & 4; float send = hi ? v[i] : v[i + 4]; float keep = hi ? v[i + 4] : v[i]; v[i] = keep + __shfl_xor(send, 4); }
; #pragma unroll
;   for (int i = 0; i < 2; i++) { bool hi = lane & 2; float send = hi ? v[i] : v[i + 2]; float keep = hi ? v[i + 2] : v[i]; v[i] = keep + __shfl_xor(send, 2); }
;   { bool hi = lane & 1; float send = hi ? v[0] : v[1]; float keep = hi ? v[1] : v[0]; v[0] = keep + __shfl_xor(send, 1); }
; __device__ __forceinline__ void gdn_chunk_item(const Params& p, int item, char* smem) {
;     ...
;       for (int t = 0; t < 64; t++) {
;         float x3 = bf2f(tp[(t + 3) * 384]);
;         float cv = x0 * w0 + x1 * w1 + x2 * w2 + x3 * w3;
;         val[t] = siluf_(cv);
;         x0 = x1; x1 = x2; x2 = x3;
;       }
;     }
;     float sq[64];
; #pragma unroll
;     for (int t = 0; t < 64; t++) sq[t] = val[t] * val[t];
;     float part = transpose_reduce64(sq, lane);
	v_add_f32_e32 v64, v64, v104
	v_cndmask_b32_e64 v104, v64, v119, s[20:21]
	s_nop 1
	v_permlane16_swap_b32_e32 v104, v104
	v_cndmask_b32_e64 v64, v119, v64, s[20:21]
	s_waitcnt lgkmcnt(0)
	v_add_f32_e32 v122, v64, v104
	v_cndmask_b32_e64 v64, v105, v65, s[18:19]
	s_nop 1
	v_permlane32_swap_b32_e32 v64, v64
	v_cndmask_b32_e64 v65, v65, v105, s[18:19]
	v_lshlrev_b32_e32 v105, 16, v101
	v_lshlrev_b32_e32 v104, 16, v100
	s_waitcnt lgkmcnt(0)
	v_add_f32_e32 v64, v65, v64
	v_cndmask_b32_e64 v65, v64, v118, s[20:21]
	s_nop 1
	v_permlane16_swap_b32_e32 v65, v65
	v_cndmask_b32_e64 v64, v118, v64, s[20:21]
	v_pk_mov_b32 v[118:119], v[104:105], v[102:103] op_sel:[1,0]
	s_waitcnt lgkmcnt(0)
	v_add_f32_e32 v123, v64, v65
	v_pk_mul_f32 v[64:65], v[2:3], v[118:119] op_sel_hi:[0,1]
	v_pk_fma_f32 v[64:65], v[0:1], v[104:105], v[64:65] op_sel_hi:[0,1,1]
	v_pk_fma_f32 v[64:65], v[4:5], v[102:103], v[64:65] op_sel_hi:[0,1,1]
	v_pk_fma_f32 v[64:65], v[6:7], v[106:107], v[64:65] op_sel_hi:[0,1,1]
	v_mul_f32_e32 v100, 0xbfb8aa3b, v64
	v_mul_f32_e32 v101, 0xbfb8aa3b, v65
	v_exp_f32_e32 v100, v100
	v_exp_f32_e32 v101, v101
	v_lshlrev_b32_e32 v103, 16, v99
	v_add_f32_e32 v100, 1.0, v100
	v_add_f32_e32 v101, 1.0, v101
	v_rcp_f32_e32 v100, v100
	v_rcp_f32_e32 v101, v101
	s_nop 0
	v_pk_mul_f32 v[64:65], v[64:65], v[100:101]
	s_nop 0
	v_pk_mul_f32 v[100:101], v[64:65], v[64:65]
	s_nop 0
	v_cndmask_b32_e64 v102, v100, v62, s[18:19]
	v_cndmask_b32_e64 v62, v62, v100, s[18:19]
	v_mov_b32_e32 v100, v102
	s_nop 1
	v_permlane32_swap_b32_e32 v100, v100
	v_lshlrev_b32_e32 v102, 16, v98
	v_pk_mov_b32 v[106:107], v[102:103], v[104:105] op_sel:[1,0]
	s_waitcnt lgkmcnt(0)
	v_add_f32_e32 v62, v62, v100
	v_cndmask_b32_e64 v100, v62, v117, s[20:21]
	s_nop 1
	v_permlane16_swap_b32_e32 v100, v100
	v_cndmask_b32_e64 v62, v117, v62, s[20:21]
	s_waitcnt lgkmcnt(0)
	v_add_f32_e32 v117, v62, v100
	v_cndmask_b32_e64 v62, v101, v63, s[18:19]
	s_nop 1
	v_permlane32_swap_b32_e32 v62, v62
	v_cndmask_b32_e64 v63, v63, v101, s[18:19]
	s_waitcnt lgkmcnt(0)
	v_add_f32_e32 v62, v63, v62
	v_cndmask_b32_e64 v63, v62, v116, s[20:21]
	s_nop 1
	v_permlane16_swap_b32_e32 v63, v63
	v_cndmask_b32_e64 v62, v116, v62, s[20:21]
	s_waitcnt lgkmcnt(0)
	v_add_f32_e32 v100, v62, v63
	v_pk_mul_f32 v[62:63], v[2:3], v[106:107] op_sel_hi:[0,1]
	v_pk_fma_f32 v[62:63], v[0:1], v[102:103], v[62:63] op_sel_hi:[0,1,1]
	v_pk_fma_f32 v[62:63], v[4:5], v[104:105], v[62:63] op_sel_hi:[0,1,1]
	v_pk_fma_f32 v[62:63], v[6:7], v[118:119], v[62:63] op_sel_hi:[0,1,1]
	v_mul_f32_e32 v98, 0xbfb8aa3b, v62
	v_mul_f32_e32 v99, 0xbfb8aa3b, v63
	v_exp_f32_e32 v98, v98
	v_exp_f32_e32 v99, v99
	v_add_f32_e32 v98, 1.0, v98
	v_add_f32_e32 v99, 1.0, v99
	v_rcp_f32_e32 v98, v98
	v_rcp_f32_e32 v99, v99
	s_nop 0
	v_pk_mul_f32 v[62:63], v[62:63], v[98:99]
	s_nop 0
	v_pk_mul_f32 v[104:105], v[62:63], v[62:63]
	s_nop 0
	v_cndmask_b32_e64 v98, v104, v94, s[18:19]
	s_nop 1
	v_permlane32_swap_b32_e32 v98, v98
	v_cndmask_b32_e64 v94, v94, v104, s[18:19]
	v_lshlrev_b32_e32 v104, 16, v51
	s_waitcnt lgkmcnt(0)
	v_add_f32_e32 v94, v94, v98
	v_cndmask_b32_e64 v98, v94, v115, s[20:21]
	s_nop 1
	v_permlane16_swap_b32_e32 v98, v98
	v_cndmask_b32_e64 v94, v115, v94, s[20:21]
	s_waitcnt lgkmcnt(0)
	v_add_f32_e32 v99, v94, v98
	v_cndmask_b32_e64 v94, v105, v95, s[18:19]
	s_nop 1
	v_permlane32_swap_b32_e32 v94, v94
	v_cndmask_b32_e64 v95, v95, v105, s[18:19]
	v_lshlrev_b32_e32 v105, 16, v53
	s_waitcnt lgkmcnt(0)
	v_add_f32_e32 v94, v95, v94
	v_cndmask_b32_e64 v95, v94, v114, s[20:21]
	s_nop 1
	v_permlane16_swap_b32_e32 v95, v95
	v_cndmask_b32_e64 v94, v114, v94, s[20:21]
	v_pk_mov_b32 v[114:115], v[104:105], v[102:103] op_sel:[1,0]
	s_waitcnt lgkmcnt(0)
	v_add_f32_e32 v98, v94, v95
	v_pk_mul_f32 v[94:95], v[2:3], v[114:115] op_sel_hi:[0,1]
	v_pk_fma_f32 v[94:95], v[0:1], v[104:105], v[94:95] op_sel_hi:[0,1,1]
	v_pk_fma_f32 v[94:95], v[4:5], v[102:103], v[94:95] op_sel_hi:[0,1,1]
	v_pk_fma_f32 v[94:95], v[6:7], v[106:107], v[94:95] op_sel_hi:[0,1,1]
	v_mul_f32_e32 v51, 0xbfb8aa3b, v94
	v_exp_f32_e32 v51, v51
	s_nop 0
	v_add_f32_e32 v51, 1.0, v51
	v_rcp_f32_e32 v102, v51
	v_mul_f32_e32 v51, 0xbfb8aa3b, v95
	v_exp_f32_e32 v51, v51
	s_nop 0
	v_add_f32_e32 v51, 1.0, v51
	v_rcp_f32_e32 v103, v51
	s_nop 0
	v_pk_mul_f32 v[94:95], v[94:95], v[102:103]
	s_nop 0
	v_pk_mul_f32 v[102:103], v[94:95], v[94:95]
	s_nop 0
	v_cndmask_b32_e64 v51, v102, v60, s[18:19]
	s_nop 1
	v_permlane32_swap_b32_e32 v51, v51
	v_cndmask_b32_e64 v53, v60, v102, s[18:19]
	v_cndmask_b32_e64 v60, v61, v103, s[18:19]
	v_lshlrev_b32_e32 v102, 16, v47
	s_waitcnt lgkmcnt(0)
	v_add_f32_e32 v51, v53, v51
	v_cndmask_b32_e64 v53, v51, v113, s[20:21]
	s_nop 1
	v_permlane16_swap_b32_e32 v53, v53
	v_cndmask_b32_e64 v51, v113, v51, s[20:21]
	s_waitcnt lgkmcnt(0)
	v_add_f32_e32 v51, v51, v53
	v_cndmask_b32_e64 v53, v51, v121, s[22:23]
	s_nop 1
	v_mov_b32_dpp v53, v53 row_ror:8 row_mask:0xf bank_mask:0xf
	v_cndmask_b32_e64 v51, v121, v51, s[22:23]
	s_waitcnt lgkmcnt(0)
	v_add_f32_e32 v51, v51, v53
	v_cndmask_b32_e64 v53, v103, v61, s[18:19]
	s_nop 1
	v_permlane32_swap_b32_e32 v53, v53
	v_lshlrev_b32_e32 v103, 16, v49
	v_pk_mov_b32 v[106:107], v[102:103], v[104:105] op_sel:[1,0]
	s_waitcnt lgkmcnt(0)
	v_add_f32_e32 v53, v60, v53
	v_cndmask_b32_e64 v60, v53, v112, s[20:21]
	s_nop 1
	v_permlane16_swap_b32_e32 v60, v60
	v_cndmask_b32_e64 v53, v112, v53, s[20:21]
	s_waitcnt lgkmcnt(0)
	v_add_f32_e32 v53, v53, v60
	v_cndmask_b32_e64 v60, v53, v120, s[22:23]
	s_nop 1
	v_mov_b32_dpp v60, v60 row_ror:8 row_mask:0xf bank_mask:0xf
	v_cndmask_b32_e64 v53, v120, v53, s[22:23]
	s_waitcnt lgkmcnt(0)
; __device__ __forceinline__ float bf2f(u16 h) { return __uint_as_float(((unsigned)h) << 16); }
; __device__ __forceinline__ float siluf_(float x) { return x * __builtin_amdgcn_rcpf(1.f + __expf(-x)); }
; __device__ __forceinline__ float transpose_reduce64(float (&v)[64], int lane) {
; #pragma unroll
;   for (int i = 0; i < 32; i++) { bool hi = lane & 32; float send = hi ? v[i] : v[i + 32]; float keep = hi ? v[i + 32] : v[i]; v[i] = keep + __shfl_xor(send, 32); }
; #pragma unroll
;   for (int i = 0; i < 16; i++) { bool hi = lane & 16; float send = hi ? v[i] : v[i + 16]; float keep = hi ? v[i + 16] : v[i]; v[i] = keep + __shfl_xor(send, 16); }
; #pragma unroll
;   for (int i = 0; i < 8; i++) { bool hi = lane & 8; float send = hi ? v[i] : v[i + 8]; float keep = hi ? v[i + 8] : v[i]; v[i] = keep + __shfl_xor(send, 8); }
; #pragma unroll
;   for (int i = 0; i < 4; i++) { bool hi = lane & 4; float send = hi ? v[i] : v[i + 4]; float keep = hi ? v[i + 4] : v[i]; v[i] = keep + __shfl_xor(send, 4); }
; #pragma unroll
;   for (int i = 0; i < 2; i++) { bool hi = lane & 2; float send = hi ? v[i] : v[i + 2]; float keep = hi ? v[i + 2] : v[i]; v[i] = keep + __shfl_xor(send, 2); }
;   { bool hi = lane & 1; float send = hi ? v[0] : v[1]; float keep = hi ? v[1] : v[0]; v[0] = keep + __shfl_xor(send, 1); }
;   return v[0];
; __device__ __forceinline__ void gdn_chunk_item(const Params& p, int item, char* smem) {
;     ...
;       for (int t = 0; t < 64; t++) {
;         float x3 = bf2f(tp[(t + 3) * 384]);
;         float cv = x0 * w0 + x1 * w1 + x2 * w2 + x3 * w3;
;         val[t] = siluf_(cv);
;         x0 = x1; x1 = x2; x2 = x3;
;       }
;     }
;     float sq[64];
; #pragma unroll
;     for (int t = 0; t < 64; t++) sq[t] = val[t] * val[t];
;     float part = transpose_reduce64(sq, lane);
;     sm_red[(type * 2 + (w & 1)) * 64 + lane] = part;
;   }
;   __syncthreads();
	v_add_f32_e32 v53, v53, v60
	v_pk_mul_f32 v[60:61], v[2:3], v[106:107] op_sel_hi:[0,1]
	v_pk_fma_f32 v[60:61], v[0:1], v[102:103], v[60:61] op_sel_hi:[0,1,1]
	v_pk_fma_f32 v[60:61], v[4:5], v[104:105], v[60:61] op_sel_hi:[0,1,1]
	v_pk_fma_f32 v[60:61], v[6:7], v[114:115], v[60:61] op_sel_hi:[0,1,1]
	v_mul_f32_e32 v47, 0xbfb8aa3b, v60
	v_exp_f32_e32 v47, v47
	s_nop 0
	v_add_f32_e32 v47, 1.0, v47
	v_rcp_f32_e32 v104, v47
	v_mul_f32_e32 v47, 0xbfb8aa3b, v61
	v_exp_f32_e32 v47, v47
	s_nop 0
	v_add_f32_e32 v47, 1.0, v47
	v_rcp_f32_e32 v105, v47
	s_nop 0
	v_pk_mul_f32 v[60:61], v[60:61], v[104:105]
	s_nop 0
	v_pk_mul_f32 v[104:105], v[60:61], v[60:61]
	s_nop 0
	v_cndmask_b32_e64 v47, v104, v58, s[18:19]
	s_nop 1
	v_permlane32_swap_b32_e32 v47, v47
	v_cndmask_b32_e64 v49, v58, v104, s[18:19]
	v_cndmask_b32_e64 v58, v59, v105, s[18:19]
	v_lshlrev_b32_e32 v104, 16, v5
	s_waitcnt lgkmcnt(0)
	v_add_f32_e32 v47, v49, v47
	v_cndmask_b32_e64 v49, v47, v111, s[20:21]
	s_nop 1
	v_permlane16_swap_b32_e32 v49, v49
	v_cndmask_b32_e64 v47, v111, v47, s[20:21]
	s_waitcnt lgkmcnt(0)
	v_add_f32_e32 v47, v47, v49
	v_cndmask_b32_e64 v49, v47, v122, s[22:23]
	s_nop 1
	v_mov_b32_dpp v49, v49 row_ror:8 row_mask:0xf bank_mask:0xf
	v_cndmask_b32_e64 v47, v122, v47, s[22:23]
	s_waitcnt lgkmcnt(0)
	v_add_f32_e32 v47, v47, v49
	v_cndmask_b32_e64 v49, v105, v59, s[18:19]
	s_nop 1
	v_permlane32_swap_b32_e32 v49, v49
	v_lshlrev_b32_e32 v105, 16, v7
	s_waitcnt lgkmcnt(0)
	v_add_f32_e32 v49, v58, v49
	v_cndmask_b32_e64 v58, v49, v110, s[20:21]
	s_nop 1
	v_permlane16_swap_b32_e32 v58, v58
	v_cndmask_b32_e64 v49, v110, v49, s[20:21]
	v_pk_mov_b32 v[110:111], v[104:105], v[102:103] op_sel:[1,0]
	s_waitcnt lgkmcnt(0)
	v_add_f32_e32 v49, v49, v58
	v_cndmask_b32_e64 v58, v49, v123, s[22:23]
	s_nop 1
	v_mov_b32_dpp v58, v58 row_ror:8 row_mask:0xf bank_mask:0xf
	v_cndmask_b32_e64 v49, v123, v49, s[22:23]
	s_waitcnt lgkmcnt(0)
	v_add_f32_e32 v49, v49, v58
	v_pk_mul_f32 v[58:59], v[2:3], v[110:111] op_sel_hi:[0,1]
	v_pk_fma_f32 v[58:59], v[0:1], v[104:105], v[58:59] op_sel_hi:[0,1,1]
	v_pk_fma_f32 v[58:59], v[4:5], v[102:103], v[58:59] op_sel_hi:[0,1,1]
	v_pk_fma_f32 v[58:59], v[6:7], v[106:107], v[58:59] op_sel_hi:[0,1,1]
	v_mul_f32_e32 v5, 0xbfb8aa3b, v58
	v_exp_f32_e32 v5, v5
	s_nop 0
	v_add_f32_e32 v5, 1.0, v5
	v_rcp_f32_e32 v102, v5
	v_mul_f32_e32 v5, 0xbfb8aa3b, v59
	v_exp_f32_e32 v5, v5
	s_nop 0
	v_add_f32_e32 v5, 1.0, v5
	v_rcp_f32_e32 v103, v5
	s_nop 0
	v_pk_mul_f32 v[58:59], v[58:59], v[102:103]
	s_nop 0
	v_pk_mul_f32 v[102:103], v[58:59], v[58:59]
	s_nop 0
	v_cndmask_b32_e64 v5, v102, v56, s[18:19]
	s_nop 1
	v_permlane32_swap_b32_e32 v5, v5
	v_cndmask_b32_e64 v7, v56, v102, s[18:19]
	v_cndmask_b32_e64 v56, v57, v103, s[18:19]
	s_waitcnt lgkmcnt(0)
	v_add_f32_e32 v5, v7, v5
	v_cndmask_b32_e64 v7, v5, v109, s[20:21]
	s_nop 1
	v_permlane16_swap_b32_e32 v7, v7
	v_cndmask_b32_e64 v5, v109, v5, s[20:21]
	s_waitcnt lgkmcnt(0)
	v_add_f32_e32 v5, v5, v7
	v_cndmask_b32_e64 v7, v5, v117, s[22:23]
	s_nop 1
	v_mov_b32_dpp v7, v7 row_ror:8 row_mask:0xf bank_mask:0xf
	v_cndmask_b32_e64 v5, v117, v5, s[22:23]
	s_waitcnt lgkmcnt(0)
	v_add_f32_e32 v5, v5, v7
	v_cndmask_b32_e64 v7, v103, v57, s[18:19]
	s_nop 1
	v_permlane32_swap_b32_e32 v7, v7
	v_lshlrev_b32_e32 v57, 16, v3
	s_waitcnt lgkmcnt(0)
	v_add_f32_e32 v7, v56, v7
	v_cndmask_b32_e64 v56, v7, v108, s[20:21]
	s_nop 1
	v_permlane16_swap_b32_e32 v56, v56
	v_cndmask_b32_e64 v7, v108, v7, s[20:21]
	s_waitcnt lgkmcnt(0)
	v_add_f32_e32 v7, v7, v56
	v_cndmask_b32_e64 v56, v7, v100, s[22:23]
	s_nop 1
	v_mov_b32_dpp v56, v56 row_ror:8 row_mask:0xf bank_mask:0xf
	v_cndmask_b32_e64 v7, v100, v7, s[22:23]
	s_waitcnt lgkmcnt(0)
	v_add_f32_e32 v7, v7, v56
	v_cndmask_b32_e64 v56, v5, v51, s[24:25]
	v_cndmask_b32_e64 v5, v51, v5, s[24:25]
	ds_bpermute_b32 v51, v197, v56
	v_lshlrev_b32_e32 v56, 16, v1
	v_pk_mov_b32 v[100:101], v[56:57], v[104:105] op_sel:[1,0]
	s_waitcnt lgkmcnt(0)
	v_add_f32_e32 v5, v5, v51
	v_cndmask_b32_e64 v51, v7, v53, s[24:25]
	ds_bpermute_b32 v51, v197, v51
	v_pk_mul_f32 v[2:3], v[2:3], v[100:101] op_sel_hi:[0,1]
	v_cndmask_b32_e64 v7, v53, v7, s[24:25]
	v_pk_fma_f32 v[0:1], v[0:1], v[56:57], v[2:3] op_sel_hi:[0,1,1]
	v_pk_fma_f32 v[0:1], v[4:5], v[104:105], v[0:1] op_sel_hi:[0,1,1]
	s_waitcnt lgkmcnt(0)
	v_add_f32_e32 v7, v7, v51
	v_pk_fma_f32 v[0:1], v[6:7], v[110:111], v[0:1] op_sel_hi:[0,1,1]
	v_mul_f32_e32 v2, 0xbfb8aa3b, v0
	v_mul_f32_e32 v3, 0xbfb8aa3b, v1
	v_exp_f32_e32 v2, v2
	v_exp_f32_e32 v3, v3
	v_add_f32_e32 v2, 1.0, v2
	v_add_f32_e32 v3, 1.0, v3
	v_rcp_f32_e32 v2, v2
	v_rcp_f32_e32 v3, v3
	s_nop 0
	v_pk_mul_f32 v[100:101], v[0:1], v[2:3]
	s_nop 0
	v_pk_mul_f32 v[0:1], v[100:101], v[100:101]
	s_nop 0
	v_cndmask_b32_e64 v2, v0, v54, s[18:19]
	s_nop 1
	v_permlane32_swap_b32_e32 v2, v2
	v_cndmask_b32_e64 v0, v54, v0, s[18:19]
	s_waitcnt lgkmcnt(0)
	v_add_f32_e32 v0, v0, v2
	v_cndmask_b32_e64 v2, v0, v97, s[20:21]
	s_nop 1
	v_permlane16_swap_b32_e32 v2, v2
	v_cndmask_b32_e64 v0, v97, v0, s[20:21]
	s_waitcnt lgkmcnt(0)
	v_add_f32_e32 v0, v0, v2
	v_cndmask_b32_e64 v2, v0, v99, s[22:23]
	s_nop 1
	v_mov_b32_dpp v2, v2 row_ror:8 row_mask:0xf bank_mask:0xf
	v_cndmask_b32_e64 v0, v99, v0, s[22:23]
	s_waitcnt lgkmcnt(0)
	v_add_f32_e32 v0, v0, v2
	v_cndmask_b32_e64 v2, v1, v55, s[18:19]
	s_nop 1
	v_permlane32_swap_b32_e32 v2, v2
	v_cndmask_b32_e64 v1, v55, v1, s[18:19]
	s_waitcnt lgkmcnt(0)
	v_add_f32_e32 v1, v1, v2
	v_cndmask_b32_e64 v2, v1, v96, s[20:21]
	s_nop 1
	v_permlane16_swap_b32_e32 v2, v2
	v_cndmask_b32_e64 v1, v96, v1, s[20:21]
	s_waitcnt lgkmcnt(0)
	v_add_f32_e32 v1, v1, v2
	v_cndmask_b32_e64 v2, v1, v98, s[22:23]
	s_nop 1
	v_mov_b32_dpp v2, v2 row_ror:8 row_mask:0xf bank_mask:0xf
	v_cndmask_b32_e64 v1, v98, v1, s[22:23]
	s_waitcnt lgkmcnt(0)
	v_add_f32_e32 v1, v1, v2
	v_cndmask_b32_e64 v2, v0, v47, s[24:25]
	ds_bpermute_b32 v2, v197, v2
	v_cndmask_b32_e64 v0, v47, v0, s[24:25]
	s_waitcnt lgkmcnt(0)
	v_add_f32_e32 v0, v0, v2
	v_cndmask_b32_e64 v2, v1, v49, s[24:25]
	ds_bpermute_b32 v2, v197, v2
	v_cndmask_b32_e64 v1, v49, v1, s[24:25]
	s_waitcnt lgkmcnt(0)
	v_add_f32_e32 v1, v1, v2
	v_cndmask_b32_e64 v2, v0, v5, s[26:27]
	s_nop 1
	v_mov_b32_dpp v2, v2 quad_perm:[2,3,0,1] row_mask:0xf bank_mask:0xf
	v_cndmask_b32_e64 v0, v5, v0, s[26:27]
	s_waitcnt lgkmcnt(0)
	v_add_f32_e32 v0, v0, v2
	v_cndmask_b32_e64 v2, v1, v7, s[26:27]
	s_nop 1
	v_mov_b32_dpp v2, v2 quad_perm:[2,3,0,1] row_mask:0xf bank_mask:0xf
	v_cndmask_b32_e64 v1, v7, v1, s[26:27]
	s_waitcnt lgkmcnt(0)
	v_add_f32_e32 v1, v1, v2
	v_cndmask_b32_e64 v2, v0, v1, s[28:29]
	v_cndmask_b32_e64 v0, v1, v0, s[28:29]
	s_nop 1
	v_mov_b32_dpp v1, v2 quad_perm:[1,0,3,2] row_mask:0xf bank_mask:0xf
	s_waitcnt lgkmcnt(0)
	v_add_f32_e32 v0, v0, v1
	ds_write_b32 v199, v0
	s_waitcnt lgkmcnt(0)
	s_barrier
; __device__ __forceinline__ u16 f2bf(float f) { return (u16)(pack2(f, f) & 0xffffu); }
; __device__ __forceinline__ void gdn_chunk_item(const Params& p, int item, char* smem) {
;     ...
;   {
;     u16* Xs = type ? Ks : Qs;
;     const float sc = type ? 1.f : 0.08838834764831845f;
; #pragma unroll
;     for (int t = 0; t < 64; t++) {
;       float rn = rsqrtf(sm_red[(type * 2) * 64 + t] + sm_red[(type * 2 + 1) * 64 + t] + EPSF) * sc;
;       val[t] *= rn;
;       Xs[t * 136 + c] = f2bf(val[t]);
;     }
;   }
	ds_read_b128 v[54:57], v203
	ds_read_b128 v[4:7], v203 offset:16
	ds_read_b128 v[0:3], v203 offset:32
	ds_read_b128 v[96:99], v203 offset:256
	s_waitcnt lgkmcnt(0)
	v_pk_add_f32 v[54:55], v[54:55], v[96:97]
	s_nop 0
	v_pk_add_f32 v[54:55], v[54:55], s[16:17] op_sel_hi:[1,0]
	v_pk_add_f32 v[56:57], v[56:57], v[98:99]
	v_mul_f32_e32 v47, 0x4b800000, v54
	v_cmp_gt_f32_e64 s[0:1], s54, v54
	v_cmp_gt_f32_e32 vcc, s54, v55
	v_pk_add_f32 v[56:57], v[56:57], s[16:17] op_sel_hi:[1,0]
	v_cndmask_b32_e64 v47, v54, v47, s[0:1]
	v_rsq_f32_e32 v54, v47
	v_mul_f32_e32 v47, 0x4b800000, v55
	v_cndmask_b32_e32 v47, v55, v47, vcc
	v_rsq_f32_e32 v55, v47
	s_nop 0
	v_pk_mul_f32 v[96:97], v[54:55], s[62:63] op_sel_hi:[1,0]
	s_nop 0
	v_cndmask_b32_e32 v55, v55, v97, vcc
	v_cndmask_b32_e64 v54, v54, v96, s[0:1]
	v_pk_mul_f32 v[54:55], v[36:37], v[54:55]
	v_cmp_gt_f32_e32 vcc, s54, v57
	v_pk_mul_f32 v[54:55], v[100:101], v[54:55]
	s_nop 0
	v_cvt_pk_bf16_f32 v47, v54, s0
	ds_write_b16 v204, v47
	v_cvt_pk_bf16_f32 v47, v55, s0
	ds_write_b16 v204, v47 offset:272
	v_mul_f32_e32 v47, 0x4b800000, v56
	v_cmp_gt_f32_e64 s[0:1], s54, v56
	s_nop 1
	v_cndmask_b32_e64 v47, v56, v47, s[0:1]
	v_rsq_f32_e32 v56, v47
	v_mul_f32_e32 v47, 0x4b800000, v57
	v_cndmask_b32_e32 v47, v57, v47, vcc
	v_rsq_f32_e32 v57, v47
	s_nop 0
	v_pk_mul_f32 v[96:97], v[56:57], s[62:63] op_sel_hi:[1,0]
	s_nop 0
	v_cndmask_b32_e32 v57, v57, v97, vcc
	v_cndmask_b32_e64 v56, v56, v96, s[0:1]
	ds_read_b128 v[96:99], v203 offset:272
	v_pk_mul_f32 v[56:57], v[36:37], v[56:57]
	s_waitcnt lgkmcnt(0)
	v_pk_add_f32 v[4:5], v[4:5], v[96:97]
	v_pk_mul_f32 v[56:57], v[58:59], v[56:57]
	v_pk_add_f32 v[4:5], v[4:5], s[16:17] op_sel_hi:[1,0]
	v_cvt_pk_bf16_f32 v47, v56, s0
	ds_write_b16 v204, v47 offset:544
	v_cvt_pk_bf16_f32 v47, v57, s0
	ds_write_b16 v204, v47 offset:816
	v_mul_f32_e32 v47, 0x4b800000, v4
	v_cmp_gt_f32_e64 s[0:1], s54, v4
	v_cmp_gt_f32_e32 vcc, s54, v5
	s_nop 0
	v_cndmask_b32_e64 v4, v4, v47, s[0:1]
	v_mul_f32_e32 v47, 0x4b800000, v5
	v_cndmask_b32_e32 v5, v5, v47, vcc
	v_rsq_f32_e32 v4, v4
	v_rsq_f32_e32 v5, v5
	s_nop 0
	v_pk_mul_f32 v[58:59], v[4:5], s[62:63] op_sel_hi:[1,0]
	s_nop 0
	v_cndmask_b32_e32 v5, v5, v59, vcc
	v_cndmask_b32_e64 v4, v4, v58, s[0:1]
	v_pk_mul_f32 v[4:5], v[36:37], v[4:5]
	s_nop 0
	v_pk_mul_f32 v[58:59], v[60:61], v[4:5]
	s_nop 0
	v_cvt_pk_bf16_f32 v4, v58, s0
	ds_write_b16 v204, v4 offset:1088
	v_cvt_pk_bf16_f32 v4, v59, s0
	ds_write_b16 v204, v4 offset:1360
	v_pk_add_f32 v[4:5], v[6:7], v[98:99]
	s_nop 0
	v_pk_add_f32 v[4:5], v[4:5], s[16:17] op_sel_hi:[1,0]
	s_nop 0
	v_mul_f32_e32 v6, 0x4b800000, v4
	v_cmp_gt_f32_e64 s[0:1], s54, v4
	v_cmp_gt_f32_e32 vcc, s54, v5
	s_nop 0
	v_cndmask_b32_e64 v4, v4, v6, s[0:1]
	v_mul_f32_e32 v6, 0x4b800000, v5
	v_cndmask_b32_e32 v5, v5, v6, vcc
	v_rsq_f32_e32 v4, v4
	v_rsq_f32_e32 v5, v5
	s_nop 0
	v_pk_mul_f32 v[6:7], v[4:5], s[62:63] op_sel_hi:[1,0]
	s_nop 0
	v_cndmask_b32_e32 v5, v5, v7, vcc
	v_cndmask_b32_e64 v4, v4, v6, s[0:1]
	v_pk_mul_f32 v[4:5], v[36:37], v[4:5]
	s_nop 0
	v_pk_mul_f32 v[60:61], v[94:95], v[4:5]
	s_nop 0
	v_cvt_pk_bf16_f32 v4, v60, s0
	ds_write_b16 v204, v4 offset:1632
	v_cvt_pk_bf16_f32 v4, v61, s0
	ds_write_b16 v204, v4 offset:1904
	ds_read_b128 v[4:7], v203 offset:288
	s_waitcnt lgkmcnt(0)
	v_pk_add_f32 v[0:1], v[0:1], v[4:5]
	s_nop 0
	v_pk_add_f32 v[0:1], v[0:1], s[16:17] op_sel_hi:[1,0]
	s_nop 0
	v_mul_f32_e32 v4, 0x4b800000, v0
	v_cmp_gt_f32_e64 s[0:1], s54, v0
	v_cmp_gt_f32_e32 vcc, s54, v1
	s_nop 0
	v_cndmask_b32_e64 v0, v0, v4, s[0:1]
	v_mul_f32_e32 v4, 0x4b800000, v1
	v_cndmask_b32_e32 v1, v1, v4, vcc
	v_rsq_f32_e32 v0, v0
	v_rsq_f32_e32 v1, v1
	s_nop 0
	v_pk_mul_f32 v[4:5], v[0:1], s[62:63] op_sel_hi:[1,0]
	s_nop 0
	v_cndmask_b32_e32 v1, v1, v5, vcc
	v_cndmask_b32_e64 v0, v0, v4, s[0:1]
	v_pk_mul_f32 v[0:1], v[36:37], v[0:1]
	s_nop 0
	v_pk_mul_f32 v[62:63], v[62:63], v[0:1]
	s_nop 0
	v_cvt_pk_bf16_f32 v0, v62, s0
	ds_write_b16 v204, v0 offset:2176
	v_cvt_pk_bf16_f32 v0, v63, s0
	ds_write_b16 v204, v0 offset:2448
	v_pk_add_f32 v[0:1], v[2:3], v[6:7]
	s_nop 0
	v_pk_add_f32 v[0:1], v[0:1], s[16:17] op_sel_hi:[1,0]
	s_nop 0
	v_mul_f32_e32 v2, 0x4b800000, v0
	v_cmp_gt_f32_e64 s[0:1], s54, v0
	v_cmp_gt_f32_e32 vcc, s54, v1
	s_nop 0
	v_cndmask_b32_e64 v0, v0, v2, s[0:1]
	v_mul_f32_e32 v2, 0x4b800000, v1
	v_cndmask_b32_e32 v1, v1, v2, vcc
	v_rsq_f32_e32 v0, v0
	v_rsq_f32_e32 v1, v1
	s_nop 0
	v_pk_mul_f32 v[2:3], v[0:1], s[62:63] op_sel_hi:[1,0]
	s_nop 0
	v_cndmask_b32_e32 v1, v1, v3, vcc
	v_cndmask_b32_e64 v0, v0, v2, s[0:1]
	v_pk_mul_f32 v[0:1], v[36:37], v[0:1]
	s_nop 0
	v_pk_mul_f32 v[64:65], v[64:65], v[0:1]
	s_nop 0
	v_cvt_pk_bf16_f32 v0, v64, s0
	ds_write_b16 v204, v0 offset:2720
	v_cvt_pk_bf16_f32 v0, v65, s0
	ds_write_b16 v204, v0 offset:2992
	ds_read_b128 v[4:7], v203 offset:48
	ds_read_b128 v[94:97], v203 offset:64
	ds_read_b128 v[0:3], v203 offset:80
	ds_read_b128 v[98:101], v203 offset:304
	s_waitcnt lgkmcnt(0)
; __device__ __forceinline__ u16 f2bf(float f) { return (u16)(pack2(f, f) & 0xffffu); }
; __device__ __forceinline__ void gdn_chunk_item(const Params& p, int item, char* smem) {
;     ...
;   {
;     u16* Xs = type ? Ks : Qs;
;     const float sc = type ? 1.f : 0.08838834764831845f;
; #pragma unroll
;     for (int t = 0; t < 64; t++) {
;       float rn = rsqrtf(sm_red[(type * 2) * 64 + t] + sm_red[(type * 2 + 1) * 64 + t] + EPSF) * sc;
;       val[t] *= rn;
;       Xs[t * 136 + c] = f2bf(val[t]);
;     }
;   }
	v_pk_add_f32 v[4:5], v[4:5], v[98:99]
	s_nop 0
	v_pk_add_f32 v[4:5], v[4:5], s[16:17] op_sel_hi:[1,0]
	s_nop 0
	v_mul_f32_e32 v47, 0x4b800000, v4
	v_cmp_gt_f32_e64 s[0:1], s54, v4
	v_cmp_gt_f32_e32 vcc, s54, v5
	s_nop 0
	v_cndmask_b32_e64 v4, v4, v47, s[0:1]
	v_mul_f32_e32 v47, 0x4b800000, v5
	v_cndmask_b32_e32 v5, v5, v47, vcc
	v_rsq_f32_e32 v4, v4
	v_rsq_f32_e32 v5, v5
	s_nop 0
	v_pk_mul_f32 v[98:99], v[4:5], s[62:63] op_sel_hi:[1,0]
	s_nop 0
	v_cndmask_b32_e32 v5, v5, v99, vcc
	v_cndmask_b32_e64 v4, v4, v98, s[0:1]
	v_pk_mul_f32 v[4:5], v[36:37], v[4:5]
	s_nop 0
	v_pk_mul_f32 v[66:67], v[66:67], v[4:5]
	s_nop 0
	v_cvt_pk_bf16_f32 v4, v66, s0
	ds_write_b16 v204, v4 offset:3264
	v_cvt_pk_bf16_f32 v4, v67, s0
	ds_write_b16 v204, v4 offset:3536
	v_pk_add_f32 v[4:5], v[6:7], v[100:101]
	s_nop 0
	v_pk_add_f32 v[4:5], v[4:5], s[16:17] op_sel_hi:[1,0]
	s_nop 0
	v_mul_f32_e32 v6, 0x4b800000, v4
	v_cmp_gt_f32_e64 s[0:1], s54, v4
	v_cmp_gt_f32_e32 vcc, s54, v5
	s_nop 0
	v_cndmask_b32_e64 v4, v4, v6, s[0:1]
	v_mul_f32_e32 v6, 0x4b800000, v5
	v_cndmask_b32_e32 v5, v5, v6, vcc
	v_rsq_f32_e32 v4, v4
	v_rsq_f32_e32 v5, v5
	s_nop 0
	v_pk_mul_f32 v[6:7], v[4:5], s[62:63] op_sel_hi:[1,0]
	s_nop 0
	v_cndmask_b32_e32 v5, v5, v7, vcc
	v_cndmask_b32_e64 v4, v4, v6, s[0:1]
	v_pk_mul_f32 v[4:5], v[36:37], v[4:5]
	s_nop 0
	v_pk_mul_f32 v[68:69], v[68:69], v[4:5]
	s_nop 0
	v_cvt_pk_bf16_f32 v4, v68, s0
	ds_write_b16 v204, v4 offset:3808
	v_cvt_pk_bf16_f32 v4, v69, s0
	ds_write_b16 v204, v4 offset:4080
	ds_read_b128 v[4:7], v203 offset:320
	s_waitcnt lgkmcnt(0)
	v_pk_add_f32 v[4:5], v[94:95], v[4:5]
	s_nop 0
	v_pk_add_f32 v[4:5], v[4:5], s[16:17] op_sel_hi:[1,0]
	s_nop 0
	v_mul_f32_e32 v47, 0x4b800000, v4
	v_cmp_gt_f32_e64 s[0:1], s54, v4
	v_cmp_gt_f32_e32 vcc, s54, v5
	s_nop 0
	v_cndmask_b32_e64 v4, v4, v47, s[0:1]
	v_mul_f32_e32 v47, 0x4b800000, v5
	v_cndmask_b32_e32 v5, v5, v47, vcc
	v_rsq_f32_e32 v4, v4
	v_rsq_f32_e32 v5, v5
	s_nop 0
	v_pk_mul_f32 v[94:95], v[4:5], s[62:63] op_sel_hi:[1,0]
	s_nop 0
	v_cndmask_b32_e32 v5, v5, v95, vcc
	v_cndmask_b32_e64 v4, v4, v94, s[0:1]
	v_pk_mul_f32 v[4:5], v[36:37], v[4:5]
	s_nop 0
	v_pk_mul_f32 v[70:71], v[70:71], v[4:5]
	s_nop 0
	v_cvt_pk_bf16_f32 v4, v70, s0
	ds_write_b16 v204, v4 offset:4352
	v_cvt_pk_bf16_f32 v4, v71, s0
	ds_write_b16 v204, v4 offset:4624
	v_pk_add_f32 v[4:5], v[96:97], v[6:7]
	s_nop 0
	v_pk_add_f32 v[4:5], v[4:5], s[16:17] op_sel_hi:[1,0]
	s_nop 0
	v_mul_f32_e32 v6, 0x4b800000, v4
	v_cmp_gt_f32_e64 s[0:1], s54, v4
	v_cmp_gt_f32_e32 vcc, s54, v5
	s_nop 0
	v_cndmask_b32_e64 v4, v4, v6, s[0:1]
	v_mul_f32_e32 v6, 0x4b800000, v5
	v_cndmask_b32_e32 v5, v5, v6, vcc
	v_rsq_f32_e32 v4, v4
	v_rsq_f32_e32 v5, v5
	s_nop 0
	v_pk_mul_f32 v[6:7], v[4:5], s[62:63] op_sel_hi:[1,0]
	s_nop 0
	v_cndmask_b32_e32 v5, v5, v7, vcc
	v_cndmask_b32_e64 v4, v4, v6, s[0:1]
	v_pk_mul_f32 v[4:5], v[36:37], v[4:5]
	s_nop 0
	v_pk_mul_f32 v[72:73], v[72:73], v[4:5]
	s_nop 0
	v_cvt_pk_bf16_f32 v4, v72, s0
	ds_write_b16 v204, v4 offset:4896
	v_cvt_pk_bf16_f32 v4, v73, s0
	ds_write_b16 v204, v4 offset:5168
	ds_read_b128 v[4:7], v203 offset:336
	s_waitcnt lgkmcnt(0)
	v_pk_add_f32 v[0:1], v[0:1], v[4:5]
	s_nop 0
	v_pk_add_f32 v[0:1], v[0:1], s[16:17] op_sel_hi:[1,0]
	s_nop 0
	v_mul_f32_e32 v4, 0x4b800000, v0
	v_cmp_gt_f32_e64 s[0:1], s54, v0
	v_cmp_gt_f32_e32 vcc, s54, v1
	s_nop 0
	v_cndmask_b32_e64 v0, v0, v4, s[0:1]
	v_mul_f32_e32 v4, 0x4b800000, v1
	v_cndmask_b32_e32 v1, v1, v4, vcc
	v_rsq_f32_e32 v0, v0
	v_rsq_f32_e32 v1, v1
	s_nop 0
	v_pk_mul_f32 v[4:5], v[0:1], s[62:63] op_sel_hi:[1,0]
	s_nop 0
	v_cndmask_b32_e32 v1, v1, v5, vcc
	v_cndmask_b32_e64 v0, v0, v4, s[0:1]
	v_pk_mul_f32 v[0:1], v[36:37], v[0:1]
	s_nop 0
	v_pk_mul_f32 v[74:75], v[74:75], v[0:1]
	s_nop 0
	v_cvt_pk_bf16_f32 v0, v74, s0
	ds_write_b16 v204, v0 offset:5440
	v_cvt_pk_bf16_f32 v0, v75, s0
	ds_write_b16 v204, v0 offset:5712
	v_pk_add_f32 v[0:1], v[2:3], v[6:7]
	s_nop 0
	v_pk_add_f32 v[0:1], v[0:1], s[16:17] op_sel_hi:[1,0]
	s_nop 0
	v_mul_f32_e32 v2, 0x4b800000, v0
	v_cmp_gt_f32_e64 s[0:1], s54, v0
	v_cmp_gt_f32_e32 vcc, s54, v1
	s_nop 0
	v_cndmask_b32_e64 v0, v0, v2, s[0:1]
	v_mul_f32_e32 v2, 0x4b800000, v1
	v_cndmask_b32_e32 v1, v1, v2, vcc
	v_rsq_f32_e32 v0, v0
	v_rsq_f32_e32 v1, v1
	s_nop 0
	v_pk_mul_f32 v[2:3], v[0:1], s[62:63] op_sel_hi:[1,0]
	s_nop 0
	v_cndmask_b32_e32 v1, v1, v3, vcc
	v_cndmask_b32_e64 v0, v0, v2, s[0:1]
	v_pk_mul_f32 v[0:1], v[36:37], v[0:1]
	s_nop 0
	v_pk_mul_f32 v[76:77], v[76:77], v[0:1]
	s_nop 0
	v_cvt_pk_bf16_f32 v0, v76, s0
	ds_write_b16 v204, v0 offset:5984
	v_cvt_pk_bf16_f32 v0, v77, s0
	ds_write_b16 v204, v0 offset:6256
	ds_read_b128 v[94:97], v203 offset:96
	ds_read_b128 v[4:7], v203 offset:112
	ds_read_b128 v[0:3], v203 offset:128
	ds_read_b128 v[98:101], v203 offset:352
	s_waitcnt lgkmcnt(0)
	v_pk_add_f32 v[94:95], v[94:95], v[98:99]
	s_nop 0
	v_pk_add_f32 v[94:95], v[94:95], s[16:17] op_sel_hi:[1,0]
	s_nop 0
	v_mul_f32_e32 v47, 0x4b800000, v94
	v_cmp_gt_f32_e64 s[0:1], s54, v94
	v_cmp_gt_f32_e32 vcc, s54, v95
	s_nop 0
	v_cndmask_b32_e64 v47, v94, v47, s[0:1]
	v_rsq_f32_e32 v94, v47
	v_mul_f32_e32 v47, 0x4b800000, v95
	v_cndmask_b32_e32 v47, v95, v47, vcc
	v_rsq_f32_e32 v95, v47
	s_nop 0
	v_pk_mul_f32 v[98:99], v[94:95], s[62:63] op_sel_hi:[1,0]
	s_nop 0
	v_cndmask_b32_e32 v95, v95, v99, vcc
	v_cndmask_b32_e64 v94, v94, v98, s[0:1]
	v_pk_mul_f32 v[94:95], v[36:37], v[94:95]
	s_nop 0
	v_pk_mul_f32 v[78:79], v[78:79], v[94:95]
	v_pk_add_f32 v[94:95], v[96:97], v[100:101]
	v_cvt_pk_bf16_f32 v47, v78, s0
	ds_write_b16 v204, v47 offset:6528
	v_cvt_pk_bf16_f32 v47, v79, s0
	v_pk_add_f32 v[94:95], v[94:95], s[16:17] op_sel_hi:[1,0]
	ds_write_b16 v204, v47 offset:6800
	v_mul_f32_e32 v47, 0x4b800000, v94
	v_cmp_gt_f32_e64 s[0:1], s54, v94
	v_cmp_gt_f32_e32 vcc, s54, v95
	s_nop 0
	v_cndmask_b32_e64 v47, v94, v47, s[0:1]
	v_rsq_f32_e32 v94, v47
	v_mul_f32_e32 v47, 0x4b800000, v95
	v_cndmask_b32_e32 v47, v95, v47, vcc
	v_rsq_f32_e32 v95, v47
	s_nop 0
	v_pk_mul_f32 v[96:97], v[94:95], s[62:63] op_sel_hi:[1,0]
	s_nop 0
	v_cndmask_b32_e32 v95, v95, v97, vcc
	v_cndmask_b32_e64 v94, v94, v96, s[0:1]
	v_pk_mul_f32 v[94:95], v[36:37], v[94:95]
	s_nop 0
	v_pk_mul_f32 v[80:81], v[80:81], v[94:95]
	ds_read_b128 v[94:97], v203 offset:368
	v_cvt_pk_bf16_f32 v47, v80, s0
	ds_write_b16 v204, v47 offset:7072
	v_cvt_pk_bf16_f32 v47, v81, s0
	ds_write_b16 v204, v47 offset:7344
	s_waitcnt lgkmcnt(2)
; __device__ __forceinline__ u16 f2bf(float f) { return (u16)(pack2(f, f) & 0xffffu); }
; __device__ __forceinline__ void gdn_chunk_item(const Params& p, int item, char* smem) {
;     ...
;   {
;     u16* Xs = type ? Ks : Qs;
;     const float sc = type ? 1.f : 0.08838834764831845f;
; #pragma unroll
;     for (int t = 0; t < 64; t++) {
;       float rn = rsqrtf(sm_red[(type * 2) * 64 + t] + sm_red[(type * 2 + 1) * 64 + t] + EPSF) * sc;
;       val[t] *= rn;
;       Xs[t * 136 + c] = f2bf(val[t]);
;     }
;   }
	v_pk_add_f32 v[4:5], v[4:5], v[94:95]
	s_nop 0
	v_pk_add_f32 v[4:5], v[4:5], s[16:17] op_sel_hi:[1,0]
	s_nop 0
	v_mul_f32_e32 v47, 0x4b800000, v4
	v_cmp_gt_f32_e64 s[0:1], s54, v4
	v_cmp_gt_f32_e32 vcc, s54, v5
	s_nop 0
	v_cndmask_b32_e64 v4, v4, v47, s[0:1]
	v_mul_f32_e32 v47, 0x4b800000, v5
	v_cndmask_b32_e32 v5, v5, v47, vcc
	v_rsq_f32_e32 v4, v4
	v_rsq_f32_e32 v5, v5
	s_nop 0
	v_pk_mul_f32 v[94:95], v[4:5], s[62:63] op_sel_hi:[1,0]
	s_nop 0
	v_cndmask_b32_e32 v5, v5, v95, vcc
	v_cndmask_b32_e64 v4, v4, v94, s[0:1]
	v_pk_mul_f32 v[4:5], v[36:37], v[4:5]
	s_nop 0
	v_pk_mul_f32 v[82:83], v[82:83], v[4:5]
	s_nop 0
	v_cvt_pk_bf16_f32 v4, v82, s0
	ds_write_b16 v204, v4 offset:7616
	v_cvt_pk_bf16_f32 v4, v83, s0
	ds_write_b16 v204, v4 offset:7888
	v_pk_add_f32 v[4:5], v[6:7], v[96:97]
	s_nop 0
	v_pk_add_f32 v[4:5], v[4:5], s[16:17] op_sel_hi:[1,0]
	s_nop 0
	v_mul_f32_e32 v6, 0x4b800000, v4
	v_cmp_gt_f32_e64 s[0:1], s54, v4
	v_cmp_gt_f32_e32 vcc, s54, v5
	s_nop 0
	v_cndmask_b32_e64 v4, v4, v6, s[0:1]
	v_mul_f32_e32 v6, 0x4b800000, v5
	v_cndmask_b32_e32 v5, v5, v6, vcc
	v_rsq_f32_e32 v4, v4
	v_rsq_f32_e32 v5, v5
	s_nop 0
	v_pk_mul_f32 v[6:7], v[4:5], s[62:63] op_sel_hi:[1,0]
	s_nop 0
	v_cndmask_b32_e32 v5, v5, v7, vcc
	v_cndmask_b32_e64 v4, v4, v6, s[0:1]
	v_pk_mul_f32 v[4:5], v[36:37], v[4:5]
	s_nop 0
	v_pk_mul_f32 v[84:85], v[84:85], v[4:5]
	s_nop 0
	v_cvt_pk_bf16_f32 v4, v84, s0
	ds_write_b16 v204, v4 offset:8160
	v_cvt_pk_bf16_f32 v4, v85, s0
	ds_write_b16 v204, v4 offset:8432
	ds_read_b128 v[4:7], v203 offset:384
	s_waitcnt lgkmcnt(0)
	v_pk_add_f32 v[0:1], v[0:1], v[4:5]
	s_nop 0
	v_pk_add_f32 v[0:1], v[0:1], s[16:17] op_sel_hi:[1,0]
	s_nop 0
	v_mul_f32_e32 v4, 0x4b800000, v0
	v_cmp_gt_f32_e64 s[0:1], s54, v0
	v_cmp_gt_f32_e32 vcc, s54, v1
	s_nop 0
	v_cndmask_b32_e64 v0, v0, v4, s[0:1]
	v_mul_f32_e32 v4, 0x4b800000, v1
	v_cndmask_b32_e32 v1, v1, v4, vcc
	v_rsq_f32_e32 v0, v0
	v_rsq_f32_e32 v1, v1
	s_nop 0
	v_pk_mul_f32 v[4:5], v[0:1], s[62:63] op_sel_hi:[1,0]
	s_nop 0
	v_cndmask_b32_e32 v1, v1, v5, vcc
	v_cndmask_b32_e64 v0, v0, v4, s[0:1]
	v_pk_mul_f32 v[0:1], v[36:37], v[0:1]
	s_nop 0
	v_pk_mul_f32 v[86:87], v[86:87], v[0:1]
	s_nop 0
	v_cvt_pk_bf16_f32 v0, v86, s0
	ds_write_b16 v204, v0 offset:8704
	v_cvt_pk_bf16_f32 v0, v87, s0
	ds_write_b16 v204, v0 offset:8976
	v_pk_add_f32 v[0:1], v[2:3], v[6:7]
	s_nop 0
	v_pk_add_f32 v[0:1], v[0:1], s[16:17] op_sel_hi:[1,0]
	s_nop 0
	v_mul_f32_e32 v2, 0x4b800000, v0
	v_cmp_gt_f32_e64 s[0:1], s54, v0
	v_cmp_gt_f32_e32 vcc, s54, v1
	s_nop 0
	v_cndmask_b32_e64 v0, v0, v2, s[0:1]
	v_mul_f32_e32 v2, 0x4b800000, v1
	v_cndmask_b32_e32 v1, v1, v2, vcc
	v_rsq_f32_e32 v0, v0
	v_rsq_f32_e32 v1, v1
	s_nop 0
	v_pk_mul_f32 v[2:3], v[0:1], s[62:63] op_sel_hi:[1,0]
	s_nop 0
	v_cndmask_b32_e32 v1, v1, v3, vcc
	v_cndmask_b32_e64 v0, v0, v2, s[0:1]
	v_pk_mul_f32 v[0:1], v[36:37], v[0:1]
	s_nop 0
	v_pk_mul_f32 v[88:89], v[88:89], v[0:1]
	s_nop 0
	v_cvt_pk_bf16_f32 v0, v88, s0
	ds_write_b16 v204, v0 offset:9248
	v_cvt_pk_bf16_f32 v0, v89, s0
	ds_write_b16 v204, v0 offset:9520
	ds_read_b128 v[4:7], v203 offset:144
	ds_read_b128 v[94:97], v203 offset:160
	ds_read_b128 v[0:3], v203 offset:176
	ds_read_b128 v[98:101], v203 offset:400
	s_waitcnt lgkmcnt(0)
	v_pk_add_f32 v[4:5], v[4:5], v[98:99]
	s_nop 0
	v_pk_add_f32 v[4:5], v[4:5], s[16:17] op_sel_hi:[1,0]
	s_nop 0
	v_mul_f32_e32 v47, 0x4b800000, v4
	v_cmp_gt_f32_e64 s[0:1], s54, v4
	v_cmp_gt_f32_e32 vcc, s54, v5
	s_nop 0
	v_cndmask_b32_e64 v4, v4, v47, s[0:1]
	v_mul_f32_e32 v47, 0x4b800000, v5
	v_cndmask_b32_e32 v5, v5, v47, vcc
	v_rsq_f32_e32 v4, v4
	v_rsq_f32_e32 v5, v5
	s_nop 0
	v_pk_mul_f32 v[98:99], v[4:5], s[62:63] op_sel_hi:[1,0]
	s_nop 0
	v_cndmask_b32_e32 v5, v5, v99, vcc
	v_cndmask_b32_e64 v4, v4, v98, s[0:1]
	v_pk_mul_f32 v[4:5], v[36:37], v[4:5]
	s_nop 0
	v_pk_mul_f32 v[90:91], v[90:91], v[4:5]
	s_nop 0
	v_cvt_pk_bf16_f32 v4, v90, s0
	ds_write_b16 v204, v4 offset:9792
	v_cvt_pk_bf16_f32 v4, v91, s0
	ds_write_b16 v204, v4 offset:10064
	v_pk_add_f32 v[4:5], v[6:7], v[100:101]
	s_nop 0
	v_pk_add_f32 v[4:5], v[4:5], s[16:17] op_sel_hi:[1,0]
	s_nop 0
	v_mul_f32_e32 v6, 0x4b800000, v4
	v_cmp_gt_f32_e64 s[0:1], s54, v4
	v_cmp_gt_f32_e32 vcc, s54, v5
	s_nop 0
	v_cndmask_b32_e64 v4, v4, v6, s[0:1]
	v_mul_f32_e32 v6, 0x4b800000, v5
	v_cndmask_b32_e32 v5, v5, v6, vcc
	v_rsq_f32_e32 v4, v4
	v_rsq_f32_e32 v5, v5
	s_nop 0
	v_pk_mul_f32 v[6:7], v[4:5], s[62:63] op_sel_hi:[1,0]
	s_nop 0
	v_cndmask_b32_e32 v5, v5, v7, vcc
	v_cndmask_b32_e64 v4, v4, v6, s[0:1]
	v_pk_mul_f32 v[4:5], v[36:37], v[4:5]
	s_nop 0
	v_pk_mul_f32 v[92:93], v[92:93], v[4:5]
	s_nop 0
	v_cvt_pk_bf16_f32 v4, v92, s0
	ds_write_b16 v204, v4 offset:10336
	v_cvt_pk_bf16_f32 v4, v93, s0
	ds_write_b16 v204, v4 offset:10608
	ds_read_b128 v[4:7], v203 offset:416
	s_waitcnt lgkmcnt(0)
	v_pk_add_f32 v[4:5], v[94:95], v[4:5]
	s_nop 0
	v_pk_add_f32 v[4:5], v[4:5], s[16:17] op_sel_hi:[1,0]
	s_nop 0
	v_mul_f32_e32 v47, 0x4b800000, v4
	v_cmp_gt_f32_e64 s[0:1], s54, v4
	v_cmp_gt_f32_e32 vcc, s54, v5
	s_nop 0
	v_cndmask_b32_e64 v4, v4, v47, s[0:1]
	v_mul_f32_e32 v47, 0x4b800000, v5
	v_cndmask_b32_e32 v5, v5, v47, vcc
	v_rsq_f32_e32 v4, v4
	v_rsq_f32_e32 v5, v5
	s_nop 0
	v_pk_mul_f32 v[94:95], v[4:5], s[62:63] op_sel_hi:[1,0]
	s_nop 0
	v_cndmask_b32_e32 v5, v5, v95, vcc
	v_cndmask_b32_e64 v4, v4, v94, s[0:1]
	v_pk_mul_f32 v[4:5], v[36:37], v[4:5]
	s_nop 0
	v_pk_mul_f32 v[94:95], v[30:31], v[4:5]
	s_nop 0
	v_cvt_pk_bf16_f32 v4, v94, s0
	ds_write_b16 v204, v4 offset:10880
	v_cvt_pk_bf16_f32 v4, v95, s0
	ds_write_b16 v204, v4 offset:11152
	v_pk_add_f32 v[4:5], v[96:97], v[6:7]
	s_nop 0
	v_pk_add_f32 v[4:5], v[4:5], s[16:17] op_sel_hi:[1,0]
	s_nop 0
	v_mul_f32_e32 v6, 0x4b800000, v4
	v_cmp_gt_f32_e64 s[0:1], s54, v4
	v_cmp_gt_f32_e32 vcc, s54, v5
	s_nop 0
	v_cndmask_b32_e64 v4, v4, v6, s[0:1]
	v_mul_f32_e32 v6, 0x4b800000, v5
	v_cndmask_b32_e32 v5, v5, v6, vcc
	v_rsq_f32_e32 v4, v4
	v_rsq_f32_e32 v5, v5
	s_nop 0
	v_pk_mul_f32 v[6:7], v[4:5], s[62:63] op_sel_hi:[1,0]
	s_nop 0
	v_cndmask_b32_e32 v5, v5, v7, vcc
	v_cndmask_b32_e64 v4, v4, v6, s[0:1]
	v_pk_mul_f32 v[4:5], v[36:37], v[4:5]
	s_nop 0
	v_pk_mul_f32 v[96:97], v[28:29], v[4:5]
	s_nop 0
	v_cvt_pk_bf16_f32 v4, v96, s0
	ds_write_b16 v204, v4 offset:11424
	v_cvt_pk_bf16_f32 v4, v97, s0
	ds_write_b16 v204, v4 offset:11696
	ds_read_b128 v[4:7], v203 offset:432
	s_waitcnt lgkmcnt(0)
; __device__ __forceinline__ u16 f2bf(float f) { return (u16)(pack2(f, f) & 0xffffu); }
; __device__ __forceinline__ void gdn_chunk_item(const Params& p, int item, char* smem) {
;     ...
;   {
;     u16* Xs = type ? Ks : Qs;
;     const float sc = type ? 1.f : 0.08838834764831845f;
; #pragma unroll
;     for (int t = 0; t < 64; t++) {
;       float rn = rsqrtf(sm_red[(type * 2) * 64 + t] + sm_red[(type * 2 + 1) * 64 + t] + EPSF) * sc;
;       val[t] *= rn;
;       Xs[t * 136 + c] = f2bf(val[t]);
;     }
;   }
	v_pk_add_f32 v[0:1], v[0:1], v[4:5]
	s_nop 0
	v_pk_add_f32 v[0:1], v[0:1], s[16:17] op_sel_hi:[1,0]
	s_nop 0
	v_mul_f32_e32 v4, 0x4b800000, v0
	v_cmp_gt_f32_e64 s[0:1], s54, v0
	v_cmp_gt_f32_e32 vcc, s54, v1
	s_nop 0
	v_cndmask_b32_e64 v0, v0, v4, s[0:1]
	v_mul_f32_e32 v4, 0x4b800000, v1
	v_cndmask_b32_e32 v1, v1, v4, vcc
	v_rsq_f32_e32 v0, v0
	v_rsq_f32_e32 v1, v1
	s_nop 0
	v_pk_mul_f32 v[4:5], v[0:1], s[62:63] op_sel_hi:[1,0]
	s_nop 0
	v_cndmask_b32_e32 v1, v1, v5, vcc
	v_cndmask_b32_e64 v0, v0, v4, s[0:1]
	v_pk_mul_f32 v[0:1], v[36:37], v[0:1]
	s_nop 0
	v_pk_mul_f32 v[98:99], v[26:27], v[0:1]
	s_nop 0
	v_cvt_pk_bf16_f32 v0, v98, s0
	ds_write_b16 v204, v0 offset:11968
	v_cvt_pk_bf16_f32 v0, v99, s0
	ds_write_b16 v204, v0 offset:12240
	v_pk_add_f32 v[0:1], v[2:3], v[6:7]
	s_nop 0
	v_pk_add_f32 v[0:1], v[0:1], s[16:17] op_sel_hi:[1,0]
	s_nop 0
	v_mul_f32_e32 v2, 0x4b800000, v0
	v_cmp_gt_f32_e64 s[0:1], s54, v0
	v_cmp_gt_f32_e32 vcc, s54, v1
	s_nop 0
	v_cndmask_b32_e64 v0, v0, v2, s[0:1]
	v_mul_f32_e32 v2, 0x4b800000, v1
	v_cndmask_b32_e32 v1, v1, v2, vcc
	v_rsq_f32_e32 v0, v0
	v_rsq_f32_e32 v1, v1
	s_nop 0
	v_pk_mul_f32 v[2:3], v[0:1], s[62:63] op_sel_hi:[1,0]
	s_nop 0
	v_cndmask_b32_e32 v1, v1, v3, vcc
	v_cndmask_b32_e64 v0, v0, v2, s[0:1]
	v_pk_mul_f32 v[0:1], v[36:37], v[0:1]
	s_nop 0
	v_pk_mul_f32 v[100:101], v[24:25], v[0:1]
	s_nop 0
	v_cvt_pk_bf16_f32 v0, v100, s0
	ds_write_b16 v204, v0 offset:12512
	v_cvt_pk_bf16_f32 v0, v101, s0
	ds_write_b16 v204, v0 offset:12784
	ds_read_b128 v[0:3], v203 offset:192
	ds_read_b128 v[4:7], v203 offset:448
	s_waitcnt lgkmcnt(0)
	v_pk_add_f32 v[0:1], v[0:1], v[4:5]
	s_nop 0
	v_pk_add_f32 v[0:1], v[0:1], s[16:17] op_sel_hi:[1,0]
	s_nop 0
	v_mul_f32_e32 v4, 0x4b800000, v0
	v_cmp_gt_f32_e64 s[0:1], s54, v0
	v_cmp_gt_f32_e32 vcc, s54, v1
	s_nop 0
	v_cndmask_b32_e64 v0, v0, v4, s[0:1]
	v_mul_f32_e32 v4, 0x4b800000, v1
	v_cndmask_b32_e32 v1, v1, v4, vcc
	v_rsq_f32_e32 v0, v0
	v_rsq_f32_e32 v1, v1
	s_nop 0
	v_pk_mul_f32 v[4:5], v[0:1], s[62:63] op_sel_hi:[1,0]
	s_nop 0
	v_cndmask_b32_e32 v1, v1, v5, vcc
	v_cndmask_b32_e64 v0, v0, v4, s[0:1]
	v_pk_mul_f32 v[0:1], v[36:37], v[0:1]
	s_nop 0
	v_pk_mul_f32 v[102:103], v[22:23], v[0:1]
	s_nop 0
	v_cvt_pk_bf16_f32 v0, v102, s0
	ds_write_b16 v204, v0 offset:13056
	v_cvt_pk_bf16_f32 v0, v103, s0
	ds_write_b16 v204, v0 offset:13328
	v_pk_add_f32 v[0:1], v[2:3], v[6:7]
	s_nop 0
	v_pk_add_f32 v[0:1], v[0:1], s[16:17] op_sel_hi:[1,0]
	s_nop 0
	v_mul_f32_e32 v2, 0x4b800000, v0
	v_cmp_gt_f32_e64 s[0:1], s54, v0
	v_cmp_gt_f32_e32 vcc, s54, v1
	s_nop 0
	v_cndmask_b32_e64 v0, v0, v2, s[0:1]
	v_mul_f32_e32 v2, 0x4b800000, v1
	v_cndmask_b32_e32 v1, v1, v2, vcc
	v_rsq_f32_e32 v0, v0
	v_rsq_f32_e32 v1, v1
	s_nop 0
	v_pk_mul_f32 v[2:3], v[0:1], s[62:63] op_sel_hi:[1,0]
	s_nop 0
	v_cndmask_b32_e32 v1, v1, v3, vcc
	v_cndmask_b32_e64 v0, v0, v2, s[0:1]
	v_pk_mul_f32 v[0:1], v[36:37], v[0:1]
	s_nop 0
	v_pk_mul_f32 v[104:105], v[20:21], v[0:1]
	s_nop 0
	v_cvt_pk_bf16_f32 v0, v104, s0
	ds_write_b16 v204, v0 offset:13600
	v_cvt_pk_bf16_f32 v0, v105, s0
	ds_write_b16 v204, v0 offset:13872
	ds_read_b128 v[0:3], v203 offset:208
	ds_read_b128 v[4:7], v203 offset:464
	s_waitcnt lgkmcnt(0)
	v_pk_add_f32 v[0:1], v[0:1], v[4:5]
	s_nop 0
	v_pk_add_f32 v[0:1], v[0:1], s[16:17] op_sel_hi:[1,0]
	s_nop 0
	v_mul_f32_e32 v4, 0x4b800000, v0
	v_cmp_gt_f32_e64 s[0:1], s54, v0
	v_cmp_gt_f32_e32 vcc, s54, v1
	s_nop 0
	v_cndmask_b32_e64 v0, v0, v4, s[0:1]
	v_mul_f32_e32 v4, 0x4b800000, v1
	v_cndmask_b32_e32 v1, v1, v4, vcc
	v_rsq_f32_e32 v0, v0
	v_rsq_f32_e32 v1, v1
	s_nop 0
	v_pk_mul_f32 v[4:5], v[0:1], s[62:63] op_sel_hi:[1,0]
	s_nop 0
	v_cndmask_b32_e32 v1, v1, v5, vcc
	v_cndmask_b32_e64 v0, v0, v4, s[0:1]
	v_pk_mul_f32 v[0:1], v[36:37], v[0:1]
	s_nop 0
	v_pk_mul_f32 v[106:107], v[18:19], v[0:1]
	s_nop 0
	v_cvt_pk_bf16_f32 v0, v106, s0
	ds_write_b16 v204, v0 offset:14144
	v_cvt_pk_bf16_f32 v0, v107, s0
	ds_write_b16 v204, v0 offset:14416
	v_pk_add_f32 v[0:1], v[2:3], v[6:7]
	s_nop 0
	v_pk_add_f32 v[0:1], v[0:1], s[16:17] op_sel_hi:[1,0]
	s_nop 0
	v_mul_f32_e32 v2, 0x4b800000, v0
	v_cmp_gt_f32_e64 s[0:1], s54, v0
	v_cmp_gt_f32_e32 vcc, s54, v1
	s_nop 0
	v_cndmask_b32_e64 v0, v0, v2, s[0:1]
	v_mul_f32_e32 v2, 0x4b800000, v1
	v_cndmask_b32_e32 v1, v1, v2, vcc
	v_rsq_f32_e32 v0, v0
	v_rsq_f32_e32 v1, v1
	s_nop 0
	v_pk_mul_f32 v[2:3], v[0:1], s[62:63] op_sel_hi:[1,0]
	s_nop 0
	v_cndmask_b32_e32 v1, v1, v3, vcc
	v_cndmask_b32_e64 v0, v0, v2, s[0:1]
	v_pk_mul_f32 v[0:1], v[36:37], v[0:1]
	s_nop 0
	v_pk_mul_f32 v[108:109], v[16:17], v[0:1]
	s_nop 0
	v_cvt_pk_bf16_f32 v0, v108, s0
	ds_write_b16 v204, v0 offset:14688
	v_cvt_pk_bf16_f32 v0, v109, s0
	ds_write_b16 v204, v0 offset:14960
	ds_read_b128 v[0:3], v203 offset:224
	ds_read_b128 v[4:7], v203 offset:480
	s_waitcnt lgkmcnt(0)
	v_pk_add_f32 v[0:1], v[0:1], v[4:5]
	s_nop 0
	v_pk_add_f32 v[0:1], v[0:1], s[16:17] op_sel_hi:[1,0]
	s_nop 0
	v_mul_f32_e32 v4, 0x4b800000, v0
	v_cmp_gt_f32_e64 s[0:1], s54, v0
	v_cmp_gt_f32_e32 vcc, s54, v1
	s_nop 0
	v_cndmask_b32_e64 v0, v0, v4, s[0:1]
	v_mul_f32_e32 v4, 0x4b800000, v1
	v_cndmask_b32_e32 v1, v1, v4, vcc
	v_rsq_f32_e32 v0, v0
	v_rsq_f32_e32 v1, v1
	s_nop 0
	v_pk_mul_f32 v[4:5], v[0:1], s[62:63] op_sel_hi:[1,0]
	s_nop 0
	v_cndmask_b32_e32 v1, v1, v5, vcc
	v_cndmask_b32_e64 v0, v0, v4, s[0:1]
	v_pk_mul_f32 v[0:1], v[36:37], v[0:1]
	s_nop 0
	v_pk_mul_f32 v[110:111], v[14:15], v[0:1]
	s_nop 0
	v_cvt_pk_bf16_f32 v0, v110, s0
	ds_write_b16 v204, v0 offset:15232
	v_cvt_pk_bf16_f32 v0, v111, s0
	ds_write_b16 v204, v0 offset:15504
	v_pk_add_f32 v[0:1], v[2:3], v[6:7]
	s_nop 0
	v_pk_add_f32 v[0:1], v[0:1], s[16:17] op_sel_hi:[1,0]
	s_nop 0
	v_mul_f32_e32 v2, 0x4b800000, v0
	v_cmp_gt_f32_e64 s[0:1], s54, v0
	v_cmp_gt_f32_e32 vcc, s54, v1
	s_nop 0
	v_cndmask_b32_e64 v0, v0, v2, s[0:1]
	v_mul_f32_e32 v2, 0x4b800000, v1
	v_cndmask_b32_e32 v1, v1, v2, vcc
	v_rsq_f32_e32 v0, v0
	v_rsq_f32_e32 v1, v1
	s_nop 0
	v_pk_mul_f32 v[2:3], v[0:1], s[62:63] op_sel_hi:[1,0]
	s_nop 0
	v_cndmask_b32_e32 v1, v1, v3, vcc
	v_cndmask_b32_e64 v0, v0, v2, s[0:1]
	v_pk_mul_f32 v[0:1], v[36:37], v[0:1]
	s_nop 0
	v_pk_mul_f32 v[112:113], v[12:13], v[0:1]
	s_nop 0
	v_cvt_pk_bf16_f32 v0, v112, s0
	ds_write_b16 v204, v0 offset:15776
	v_cvt_pk_bf16_f32 v0, v113, s0
	ds_write_b16 v204, v0 offset:16048
	ds_read_b128 v[0:3], v203 offset:240
	ds_read_b128 v[4:7], v203 offset:496
	s_waitcnt lgkmcnt(0)
; __device__ __forceinline__ u16 f2bf(float f) { return (u16)(pack2(f, f) & 0xffffu); }
; __device__ __forceinline__ float bf2f(u16 h) { return __uint_as_float(((unsigned)h) << 16); }
; __device__ __forceinline__ float siluf_(float x) { return x * __builtin_amdgcn_rcpf(1.f + __expf(-x)); }
; __device__ __forceinline__ void gdn_chunk_item(const Params& p, int item, char* smem) {
;     ...
;       val[t] *= rn;
;       Xs[t * 136 + c] = f2bf(val[t]);
;     }
;   }
;   {
;     const u16* tile = (const u16*)Xs;
;   if (type == 0) {
;     const int col = 1024 + h * 128 + c;
;     const float w0 = p.conv_w[col], w1 = p.conv_w[1536 + col], w2 = p.conv_w[3072 + col], w3 = p.conv_w[4608 + col];
;     const u16* tp = tile + 256 + c;
;     float x0 = bf2f(tp[0]), x1 = bf2f(tp[384]), x2 = bf2f(tp[768]);
; #pragma unroll
;     for (int t = 0; t < 64; t++) {
;       float x3 = bf2f(tp[(t + 3) * 384]);
;       float cv = x0 * w0 + x1 * w1 + x2 * w2 + x3 * w3;
;       vv[t] = siluf_(cv) * sm_bt[t];
	v_pk_add_f32 v[0:1], v[0:1], v[4:5]
	s_nop 0
	v_pk_add_f32 v[0:1], v[0:1], s[16:17] op_sel_hi:[1,0]
	s_nop 0
	v_mul_f32_e32 v4, 0x4b800000, v0
	v_cmp_gt_f32_e64 s[0:1], s54, v0
	v_cmp_gt_f32_e32 vcc, s54, v1
	s_nop 0
	v_cndmask_b32_e64 v0, v0, v4, s[0:1]
	v_mul_f32_e32 v4, 0x4b800000, v1
	v_cndmask_b32_e32 v1, v1, v4, vcc
	v_rsq_f32_e32 v0, v0
	v_rsq_f32_e32 v1, v1
	s_nop 0
	v_pk_mul_f32 v[4:5], v[0:1], s[62:63] op_sel_hi:[1,0]
	s_nop 0
	v_cndmask_b32_e32 v1, v1, v5, vcc
	v_cndmask_b32_e64 v0, v0, v4, s[0:1]
	v_pk_mul_f32 v[0:1], v[36:37], v[0:1]
	s_nop 0
	v_pk_mul_f32 v[114:115], v[8:9], v[0:1]
	s_nop 0
	v_cvt_pk_bf16_f32 v0, v114, s0
	ds_write_b16 v204, v0 offset:16320
	v_cvt_pk_bf16_f32 v0, v115, s0
	ds_write_b16 v204, v0 offset:16592
	v_pk_add_f32 v[0:1], v[2:3], v[6:7]
	s_nop 0
	v_pk_add_f32 v[0:1], v[0:1], s[16:17] op_sel_hi:[1,0]
	s_nop 0
	v_mul_f32_e32 v2, 0x4b800000, v0
	v_cmp_gt_f32_e64 s[0:1], s54, v0
	v_cmp_gt_f32_e32 vcc, s54, v1
	s_nop 0
	v_cndmask_b32_e64 v0, v0, v2, s[0:1]
	v_mul_f32_e32 v2, 0x4b800000, v1
	v_cndmask_b32_e32 v1, v1, v2, vcc
	v_rsq_f32_e32 v0, v0
	v_rsq_f32_e32 v1, v1
	s_nop 0
	v_pk_mul_f32 v[2:3], v[0:1], s[62:63] op_sel_hi:[1,0]
	s_nop 0
	v_cndmask_b32_e32 v1, v1, v3, vcc
	v_cndmask_b32_e64 v0, v0, v2, s[0:1]
	v_pk_mul_f32 v[0:1], v[36:37], v[0:1]
	s_nop 0
	v_pk_mul_f32 v[116:117], v[10:11], v[0:1]
	s_nop 0
	v_cvt_pk_bf16_f32 v0, v116, s0
	ds_write_b16 v204, v0 offset:16864
	v_cvt_pk_bf16_f32 v0, v117, s0
	ds_write_b16 v204, v0 offset:17136
	s_and_saveexec_b64 s[36:37], s[30:31]
	s_cbranch_execz .LBB0_806
	v_or_b32_e32 v0, s72, v237
	v_readlane_b32 s0, v254, 3
	v_lshlrev_b32_e32 v0, 2, v0
	v_mov_b32_e32 v1, v35
	v_readlane_b32 s4, v254, 7
	v_readlane_b32 s5, v254, 8
	v_readlane_b32 s1, v254, 4
	v_readlane_b32 s2, v254, 5
	v_lshl_add_u64 v[0:1], s[4:5], 0, v[0:1]
	v_add_co_u32_e32 v2, vcc, 0x1000, v0
	v_readlane_b32 s3, v254, 6
	s_nop 0
	v_addc_co_u32_e32 v3, vcc, 0, v1, vcc
	global_load_dword v8, v[2:3], off
	v_add_co_u32_e32 v2, vcc, 0x2000, v0
	v_readlane_b32 s6, v254, 9
	s_nop 0
	v_addc_co_u32_e32 v3, vcc, 0, v1, vcc
	global_load_dword v10, v[2:3], off offset:2048
	v_add_co_u32_e32 v2, vcc, 0x4000, v0
	v_readlane_b32 s7, v254, 10
	s_nop 0
	v_addc_co_u32_e32 v3, vcc, 0, v1, vcc
	v_add_co_u32_e32 v0, vcc, 0x5000, v0
	global_load_dword v12, v[2:3], off
	s_nop 0
	v_addc_co_u32_e32 v1, vcc, 0, v1, vcc
	global_load_dword v14, v[0:1], off offset:2048
	ds_read_u16 v0, v205 offset:23040
	ds_read_u16 v1, v205 offset:23808
	v_readlane_b32 s8, v254, 11
	v_readlane_b32 s9, v254, 12
	v_readlane_b32 s10, v254, 13
	s_waitcnt lgkmcnt(1)
	v_lshlrev_b32_e32 v20, 16, v0
	ds_read_u16 v0, v205 offset:24576
	s_waitcnt lgkmcnt(1)
	v_lshlrev_b32_e32 v21, 16, v1
	v_mov_b32_e32 v22, v21
	v_readlane_b32 s11, v254, 14
	v_readlane_b32 s12, v254, 15
	s_waitcnt lgkmcnt(0)
	v_lshlrev_b32_e32 v23, 16, v0
	ds_read_u16 v0, v205 offset:26112
	ds_read_u16 v1, v205 offset:25344
	v_mov_b32_e32 v16, v23
	v_readlane_b32 s13, v254, 16
	v_readlane_b32 s14, v254, 17
	s_waitcnt lgkmcnt(1)
	v_lshlrev_b32_e32 v19, 16, v0
	s_waitcnt lgkmcnt(0)
	v_lshlrev_b32_e32 v17, 16, v1
	ds_read_u16 v0, v205 offset:21504
	ds_read_u16 v1, v205 offset:22272
	v_mov_b32_e32 v18, v17
	v_readlane_b32 s15, v254, 18
	s_waitcnt lgkmcnt(1)
	v_lshlrev_b32_e32 v24, 16, v0
	s_waitcnt lgkmcnt(0)
	v_lshlrev_b32_e32 v25, 16, v1
	ds_read_b128 v[0:3], v35 offset:64880
	ds_read_u16 v4, v205 offset:19968
	ds_read_u16 v5, v205 offset:20736
	s_waitcnt lgkmcnt(1)
	v_lshlrev_b32_e32 v26, 16, v4
	s_waitcnt lgkmcnt(0)
	v_lshlrev_b32_e32 v27, 16, v5
	ds_read_b128 v[4:7], v35 offset:64864
	ds_read_u16 v9, v205 offset:18432
	ds_read_u16 v11, v205 offset:19200
	s_waitcnt lgkmcnt(1)
	v_lshlrev_b32_e32 v150, 16, v9
	s_waitcnt lgkmcnt(0)
	v_lshlrev_b32_e32 v151, 16, v11
	ds_read_u16 v9, v205 offset:16896
	ds_read_u16 v11, v205 offset:17664
	s_waitcnt lgkmcnt(1)
	v_lshlrev_b32_e32 v148, 16, v9
	s_waitcnt lgkmcnt(0)
	v_lshlrev_b32_e32 v149, 16, v11
	ds_read_b128 v[28:31], v35 offset:64848
	ds_read_u16 v9, v205 offset:15360
	ds_read_u16 v11, v205 offset:16128
	s_waitcnt lgkmcnt(1)
	v_lshlrev_b32_e32 v146, 16, v9
	s_waitcnt lgkmcnt(0)
	v_lshlrev_b32_e32 v147, 16, v11
	ds_read_u16 v9, v205 offset:13824
	ds_read_u16 v11, v205 offset:14592
	s_waitcnt lgkmcnt(1)
	v_lshlrev_b32_e32 v152, 16, v9
	s_waitcnt lgkmcnt(0)
	v_lshlrev_b32_e32 v153, 16, v11
	ds_read_b128 v[142:145], v35 offset:64832
	ds_read_u16 v9, v205 offset:12288
	ds_read_u16 v11, v205 offset:13056
	s_waitcnt lgkmcnt(1)
	v_lshlrev_b32_e32 v154, 16, v9
	s_waitcnt lgkmcnt(0)
	v_lshlrev_b32_e32 v155, 16, v11
	ds_read_u16 v9, v205 offset:10752
	ds_read_u16 v11, v205 offset:11520
	s_waitcnt lgkmcnt(1)
	v_lshlrev_b32_e32 v156, 16, v9
	s_waitcnt lgkmcnt(0)
	v_lshlrev_b32_e32 v157, 16, v11
	ds_read_b128 v[118:121], v35 offset:64768
	ds_read_b128 v[122:125], v35 offset:64784
	ds_read_b128 v[126:129], v35 offset:64800
	ds_read_b128 v[130:133], v35 offset:64816
	ds_read_u16 v9, v205 offset:9216
	ds_read_u16 v11, v205 offset:9984
	s_waitcnt lgkmcnt(1)
	v_lshlrev_b32_e32 v158, 16, v9
	s_waitcnt lgkmcnt(0)
	v_lshlrev_b32_e32 v159, 16, v11
	ds_read_u16 v9, v205 offset:7680
	ds_read_u16 v11, v205 offset:8448
	s_waitcnt lgkmcnt(1)
	v_lshlrev_b32_e32 v160, 16, v9
	s_waitcnt lgkmcnt(0)
	v_lshlrev_b32_e32 v161, 16, v11
	ds_read_u16 v9, v205 offset:6144
	ds_read_u16 v11, v205 offset:6912
	s_waitcnt lgkmcnt(1)
	v_lshlrev_b32_e32 v162, 16, v9
	s_waitcnt lgkmcnt(0)
	v_lshlrev_b32_e32 v163, 16, v11
	ds_read_u16 v9, v205 offset:4608
	ds_read_u16 v11, v205 offset:5376
	s_waitcnt lgkmcnt(1)
	v_lshlrev_b32_e32 v164, 16, v9
	s_waitcnt lgkmcnt(0)
; __device__ __forceinline__ float bf2f(u16 h) { return __uint_as_float(((unsigned)h) << 16); }
; __device__ __forceinline__ float siluf_(float x) { return x * __builtin_amdgcn_rcpf(1.f + __expf(-x)); }
; __device__ __forceinline__ void gdn_chunk_item(const Params& p, int item, char* smem) {
;     ...
; #pragma unroll
;     for (int t = 0; t < 64; t++) {
;       float x3 = bf2f(tp[(t + 3) * 384]);
;       float cv = x0 * w0 + x1 * w1 + x2 * w2 + x3 * w3;
;       vv[t] = siluf_(cv) * sm_bt[t];
;       x0 = x1; x1 = x2; x2 = x3;
;     }
	v_lshlrev_b32_e32 v165, 16, v11
	ds_read_u16 v9, v205 offset:3072
	ds_read_u16 v11, v205 offset:3840
	s_waitcnt lgkmcnt(1)
	v_lshlrev_b32_e32 v166, 16, v9
	s_waitcnt lgkmcnt(0)
	v_lshlrev_b32_e32 v167, 16, v11
	ds_read_u16 v9, v205 offset:1536
	ds_read_u16 v11, v205 offset:2304
	s_waitcnt lgkmcnt(1)
	v_lshlrev_b32_e32 v168, 16, v9
	s_waitcnt lgkmcnt(0)
	v_lshlrev_b32_e32 v169, 16, v11
	ds_read_u16 v9, v205
	ds_read_u16 v11, v205 offset:768
	v_pk_mov_b32 v[172:173], v[168:169], v[166:167] op_sel:[1,0]
	s_waitcnt lgkmcnt(1)
	v_lshlrev_b32_e32 v170, 16, v9
	s_waitcnt lgkmcnt(0)
	v_lshlrev_b32_e32 v171, 16, v11
	v_pk_mov_b32 v[174:175], v[170:171], v[168:169] op_sel:[1,0]
	s_waitcnt vmcnt(2)
	v_pk_mul_f32 v[174:175], v[10:11], v[174:175] op_sel_hi:[0,1]
	v_pk_fma_f32 v[170:171], v[8:9], v[170:171], v[174:175] op_sel_hi:[0,1,1]
	s_waitcnt vmcnt(1)
	v_pk_fma_f32 v[170:171], v[12:13], v[168:169], v[170:171] op_sel_hi:[0,1,1]
	s_waitcnt vmcnt(0)
	v_pk_fma_f32 v[170:171], v[14:15], v[172:173], v[170:171] op_sel_hi:[0,1,1]
	v_mul_f32_e32 v9, 0xbfb8aa3b, v170
	v_exp_f32_e32 v9, v9
	v_pk_mul_f32 v[172:173], v[10:11], v[172:173] op_sel_hi:[0,1]
	v_add_f32_e32 v9, 1.0, v9
	v_rcp_f32_e32 v174, v9
	v_mul_f32_e32 v9, 0xbfb8aa3b, v171
	v_exp_f32_e32 v9, v9
	s_nop 0
	v_add_f32_e32 v9, 1.0, v9
	v_rcp_f32_e32 v175, v9
	v_pk_fma_f32 v[168:169], v[8:9], v[168:169], v[172:173] op_sel_hi:[0,1,1]
	v_pk_fma_f32 v[168:169], v[12:13], v[166:167], v[168:169] op_sel_hi:[0,1,1]
	v_pk_mul_f32 v[170:171], v[170:171], v[174:175]
	s_nop 0
	v_pk_mul_f32 v[118:119], v[118:119], v[170:171]
	v_pk_mov_b32 v[170:171], v[166:167], v[164:165] op_sel:[1,0]
	s_nop 0
	v_pk_fma_f32 v[168:169], v[14:15], v[170:171], v[168:169] op_sel_hi:[0,1,1]
	v_mul_f32_e32 v9, 0xbfb8aa3b, v168
	v_exp_f32_e32 v9, v9
	v_pk_mul_f32 v[170:171], v[10:11], v[170:171] op_sel_hi:[0,1]
	v_add_f32_e32 v9, 1.0, v9
	v_rcp_f32_e32 v172, v9
	v_mul_f32_e32 v9, 0xbfb8aa3b, v169
	v_exp_f32_e32 v9, v9
	s_nop 0
	v_add_f32_e32 v9, 1.0, v9
	v_rcp_f32_e32 v173, v9
	v_pk_fma_f32 v[166:167], v[8:9], v[166:167], v[170:171] op_sel_hi:[0,1,1]
	v_pk_fma_f32 v[166:167], v[12:13], v[164:165], v[166:167] op_sel_hi:[0,1,1]
	v_pk_mul_f32 v[168:169], v[168:169], v[172:173]
	s_nop 0
	v_pk_mul_f32 v[120:121], v[120:121], v[168:169]
	v_pk_mov_b32 v[168:169], v[164:165], v[162:163] op_sel:[1,0]
	s_nop 0
	v_pk_fma_f32 v[166:167], v[14:15], v[168:169], v[166:167] op_sel_hi:[0,1,1]
	v_mul_f32_e32 v9, 0xbfb8aa3b, v166
	v_exp_f32_e32 v9, v9
	v_pk_mul_f32 v[168:169], v[10:11], v[168:169] op_sel_hi:[0,1]
	v_add_f32_e32 v9, 1.0, v9
	v_rcp_f32_e32 v170, v9
	v_mul_f32_e32 v9, 0xbfb8aa3b, v167
	v_exp_f32_e32 v9, v9
	s_nop 0
	v_add_f32_e32 v9, 1.0, v9
	v_rcp_f32_e32 v171, v9
	v_pk_fma_f32 v[164:165], v[8:9], v[164:165], v[168:169] op_sel_hi:[0,1,1]
	v_pk_fma_f32 v[164:165], v[12:13], v[162:163], v[164:165] op_sel_hi:[0,1,1]
	v_pk_mul_f32 v[166:167], v[166:167], v[170:171]
	s_nop 0
	v_pk_mul_f32 v[122:123], v[122:123], v[166:167]
	v_pk_mov_b32 v[166:167], v[162:163], v[160:161] op_sel:[1,0]
	s_nop 0
	v_pk_fma_f32 v[164:165], v[14:15], v[166:167], v[164:165] op_sel_hi:[0,1,1]
	v_mul_f32_e32 v9, 0xbfb8aa3b, v164
	v_exp_f32_e32 v9, v9
	v_pk_mul_f32 v[166:167], v[10:11], v[166:167] op_sel_hi:[0,1]
	v_add_f32_e32 v9, 1.0, v9
	v_rcp_f32_e32 v168, v9
	v_mul_f32_e32 v9, 0xbfb8aa3b, v165
	v_exp_f32_e32 v9, v9
	s_nop 0
	v_add_f32_e32 v9, 1.0, v9
	v_rcp_f32_e32 v169, v9
	v_pk_fma_f32 v[162:163], v[8:9], v[162:163], v[166:167] op_sel_hi:[0,1,1]
	v_pk_fma_f32 v[162:163], v[12:13], v[160:161], v[162:163] op_sel_hi:[0,1,1]
	v_pk_mul_f32 v[164:165], v[164:165], v[168:169]
	s_nop 0
	v_pk_mul_f32 v[124:125], v[124:125], v[164:165]
	v_pk_mov_b32 v[164:165], v[160:161], v[158:159] op_sel:[1,0]
	s_nop 0
	v_pk_fma_f32 v[162:163], v[14:15], v[164:165], v[162:163] op_sel_hi:[0,1,1]
	v_mul_f32_e32 v9, 0xbfb8aa3b, v162
	v_exp_f32_e32 v9, v9
	v_pk_mul_f32 v[164:165], v[10:11], v[164:165] op_sel_hi:[0,1]
	v_add_f32_e32 v9, 1.0, v9
	v_rcp_f32_e32 v166, v9
	v_mul_f32_e32 v9, 0xbfb8aa3b, v163
	v_exp_f32_e32 v9, v9
	s_nop 0
	v_add_f32_e32 v9, 1.0, v9
	v_rcp_f32_e32 v167, v9
	v_pk_fma_f32 v[160:161], v[8:9], v[160:161], v[164:165] op_sel_hi:[0,1,1]
	v_pk_fma_f32 v[160:161], v[12:13], v[158:159], v[160:161] op_sel_hi:[0,1,1]
	v_pk_mul_f32 v[162:163], v[162:163], v[166:167]
	s_nop 0
	v_pk_mul_f32 v[126:127], v[126:127], v[162:163]
	v_pk_mov_b32 v[162:163], v[158:159], v[156:157] op_sel:[1,0]
	s_nop 0
	v_pk_fma_f32 v[160:161], v[14:15], v[162:163], v[160:161] op_sel_hi:[0,1,1]
	v_mul_f32_e32 v9, 0xbfb8aa3b, v160
	v_exp_f32_e32 v9, v9
	v_pk_mul_f32 v[162:163], v[10:11], v[162:163] op_sel_hi:[0,1]
	v_add_f32_e32 v9, 1.0, v9
	v_rcp_f32_e32 v164, v9
	v_mul_f32_e32 v9, 0xbfb8aa3b, v161
	v_exp_f32_e32 v9, v9
	s_nop 0
	v_add_f32_e32 v9, 1.0, v9
	v_rcp_f32_e32 v165, v9
	v_pk_fma_f32 v[158:159], v[8:9], v[158:159], v[162:163] op_sel_hi:[0,1,1]
	v_pk_fma_f32 v[158:159], v[12:13], v[156:157], v[158:159] op_sel_hi:[0,1,1]
	v_pk_mul_f32 v[160:161], v[160:161], v[164:165]
	s_nop 0
	v_pk_mul_f32 v[128:129], v[128:129], v[160:161]
	v_pk_mov_b32 v[160:161], v[156:157], v[154:155] op_sel:[1,0]
	s_nop 0
	v_pk_fma_f32 v[158:159], v[14:15], v[160:161], v[158:159] op_sel_hi:[0,1,1]
	v_mul_f32_e32 v9, 0xbfb8aa3b, v158
	v_exp_f32_e32 v9, v9
	v_pk_mul_f32 v[160:161], v[10:11], v[160:161] op_sel_hi:[0,1]
	v_add_f32_e32 v9, 1.0, v9
	v_rcp_f32_e32 v162, v9
	v_mul_f32_e32 v9, 0xbfb8aa3b, v159
	v_exp_f32_e32 v9, v9
	s_nop 0
	v_add_f32_e32 v9, 1.0, v9
	v_rcp_f32_e32 v163, v9
	v_pk_fma_f32 v[156:157], v[8:9], v[156:157], v[160:161] op_sel_hi:[0,1,1]
	v_pk_fma_f32 v[156:157], v[12:13], v[154:155], v[156:157] op_sel_hi:[0,1,1]
; __device__ __forceinline__ float bf2f(u16 h) { return __uint_as_float(((unsigned)h) << 16); }
; __device__ __forceinline__ float siluf_(float x) { return x * __builtin_amdgcn_rcpf(1.f + __expf(-x)); }
; __device__ __forceinline__ void gdn_chunk_item(const Params& p, int item, char* smem) {
;     ...
; #pragma unroll
;     for (int t = 0; t < 64; t++) {
;       float x3 = bf2f(tp[(t + 3) * 384]);
;       float cv = x0 * w0 + x1 * w1 + x2 * w2 + x3 * w3;
;       vv[t] = siluf_(cv) * sm_bt[t];
;       x0 = x1; x1 = x2; x2 = x3;
;     }
	v_pk_mul_f32 v[158:159], v[158:159], v[162:163]
	s_nop 0
	v_pk_mul_f32 v[130:131], v[130:131], v[158:159]
	v_pk_mov_b32 v[158:159], v[154:155], v[152:153] op_sel:[1,0]
	s_nop 0
	v_pk_fma_f32 v[156:157], v[14:15], v[158:159], v[156:157] op_sel_hi:[0,1,1]
	v_mul_f32_e32 v9, 0xbfb8aa3b, v156
	v_exp_f32_e32 v9, v9
	v_pk_mul_f32 v[158:159], v[10:11], v[158:159] op_sel_hi:[0,1]
	v_add_f32_e32 v9, 1.0, v9
	v_rcp_f32_e32 v160, v9
	v_mul_f32_e32 v9, 0xbfb8aa3b, v157
	v_exp_f32_e32 v9, v9
	s_nop 0
	v_add_f32_e32 v9, 1.0, v9
	v_rcp_f32_e32 v161, v9
	v_pk_fma_f32 v[154:155], v[8:9], v[154:155], v[158:159] op_sel_hi:[0,1,1]
	v_pk_fma_f32 v[154:155], v[12:13], v[152:153], v[154:155] op_sel_hi:[0,1,1]
	v_pk_mul_f32 v[156:157], v[156:157], v[160:161]
	s_nop 0
	v_pk_mul_f32 v[132:133], v[132:133], v[156:157]
	v_pk_mov_b32 v[156:157], v[152:153], v[146:147] op_sel:[1,0]
	s_nop 0
	v_pk_fma_f32 v[154:155], v[14:15], v[156:157], v[154:155] op_sel_hi:[0,1,1]
	v_mul_f32_e32 v9, 0xbfb8aa3b, v154
	v_exp_f32_e32 v9, v9
	v_pk_mul_f32 v[156:157], v[10:11], v[156:157] op_sel_hi:[0,1]
	v_add_f32_e32 v9, 1.0, v9
	v_rcp_f32_e32 v158, v9
	v_mul_f32_e32 v9, 0xbfb8aa3b, v155
	v_exp_f32_e32 v9, v9
	s_nop 0
	v_add_f32_e32 v9, 1.0, v9
	v_rcp_f32_e32 v159, v9
	v_pk_fma_f32 v[152:153], v[8:9], v[152:153], v[156:157] op_sel_hi:[0,1,1]
	v_pk_fma_f32 v[152:153], v[12:13], v[146:147], v[152:153] op_sel_hi:[0,1,1]
	v_pk_mul_f32 v[154:155], v[154:155], v[158:159]
	s_nop 0
	v_pk_mul_f32 v[142:143], v[142:143], v[154:155]
	v_pk_mov_b32 v[154:155], v[146:147], v[148:149] op_sel:[1,0]
	s_nop 0
	v_pk_fma_f32 v[152:153], v[14:15], v[154:155], v[152:153] op_sel_hi:[0,1,1]
	v_mul_f32_e32 v9, 0xbfb8aa3b, v152
	v_exp_f32_e32 v9, v9
	v_pk_mul_f32 v[154:155], v[10:11], v[154:155] op_sel_hi:[0,1]
	v_add_f32_e32 v9, 1.0, v9
	v_rcp_f32_e32 v156, v9
	v_mul_f32_e32 v9, 0xbfb8aa3b, v153
	v_exp_f32_e32 v9, v9
	s_nop 0
	v_add_f32_e32 v9, 1.0, v9
	v_rcp_f32_e32 v157, v9
	v_pk_fma_f32 v[146:147], v[8:9], v[146:147], v[154:155] op_sel_hi:[0,1,1]
	v_pk_fma_f32 v[146:147], v[12:13], v[148:149], v[146:147] op_sel_hi:[0,1,1]
	v_pk_mul_f32 v[152:153], v[152:153], v[156:157]
	s_nop 0
	v_pk_mul_f32 v[144:145], v[144:145], v[152:153]
	v_pk_mov_b32 v[152:153], v[148:149], v[150:151] op_sel:[1,0]
	s_nop 0
	v_pk_fma_f32 v[146:147], v[14:15], v[152:153], v[146:147] op_sel_hi:[0,1,1]
	v_mul_f32_e32 v9, 0xbfb8aa3b, v146
	v_exp_f32_e32 v9, v9
	v_pk_mul_f32 v[152:153], v[10:11], v[152:153] op_sel_hi:[0,1]
	v_add_f32_e32 v9, 1.0, v9
	v_rcp_f32_e32 v154, v9
	v_mul_f32_e32 v9, 0xbfb8aa3b, v147
	v_exp_f32_e32 v9, v9
	s_nop 0
	v_add_f32_e32 v9, 1.0, v9
	v_rcp_f32_e32 v155, v9
	v_pk_fma_f32 v[148:149], v[8:9], v[148:149], v[152:153] op_sel_hi:[0,1,1]
	v_pk_fma_f32 v[148:149], v[12:13], v[150:151], v[148:149] op_sel_hi:[0,1,1]
	v_pk_mul_f32 v[146:147], v[146:147], v[154:155]
	s_nop 0
	v_pk_mul_f32 v[146:147], v[28:29], v[146:147]
	v_pk_mov_b32 v[28:29], v[150:151], v[26:27] op_sel:[1,0]
	s_nop 0
	v_pk_fma_f32 v[148:149], v[14:15], v[28:29], v[148:149] op_sel_hi:[0,1,1]
	v_mul_f32_e32 v9, 0xbfb8aa3b, v148
	v_exp_f32_e32 v9, v9
	v_pk_mul_f32 v[28:29], v[10:11], v[28:29] op_sel_hi:[0,1]
	v_add_f32_e32 v9, 1.0, v9
	v_rcp_f32_e32 v152, v9
	v_mul_f32_e32 v9, 0xbfb8aa3b, v149
	v_exp_f32_e32 v9, v9
	s_nop 0
	v_add_f32_e32 v9, 1.0, v9
	v_rcp_f32_e32 v153, v9
	v_pk_fma_f32 v[28:29], v[8:9], v[150:151], v[28:29] op_sel_hi:[0,1,1]
	v_pk_fma_f32 v[28:29], v[12:13], v[26:27], v[28:29] op_sel_hi:[0,1,1]
	v_pk_mul_f32 v[148:149], v[148:149], v[152:153]
	s_nop 0
	v_pk_mul_f32 v[148:149], v[30:31], v[148:149]
	v_pk_mov_b32 v[30:31], v[26:27], v[24:25] op_sel:[1,0]
	s_nop 0
	v_pk_fma_f32 v[28:29], v[14:15], v[30:31], v[28:29] op_sel_hi:[0,1,1]
	v_mul_f32_e32 v9, 0xbfb8aa3b, v28
	v_exp_f32_e32 v9, v9
	s_nop 0
	v_add_f32_e32 v9, 1.0, v9
	v_rcp_f32_e32 v150, v9
	v_mul_f32_e32 v9, 0xbfb8aa3b, v29
	v_exp_f32_e32 v9, v9
	s_nop 0
	v_add_f32_e32 v9, 1.0, v9
	v_rcp_f32_e32 v151, v9
	s_nop 0
	v_pk_mul_f32 v[28:29], v[28:29], v[150:151]
	s_nop 0
	v_pk_mul_f32 v[150:151], v[4:5], v[28:29]
	v_pk_mul_f32 v[28:29], v[10:11], v[30:31] op_sel_hi:[0,1]
	v_pk_fma_f32 v[26:27], v[8:9], v[26:27], v[28:29] op_sel_hi:[0,1,1]
	v_pk_mov_b32 v[4:5], v[24:25], v[20:21] op_sel:[1,0]
	v_pk_fma_f32 v[26:27], v[12:13], v[24:25], v[26:27] op_sel_hi:[0,1,1]
	v_pk_fma_f32 v[26:27], v[14:15], v[4:5], v[26:27] op_sel_hi:[0,1,1]
	v_mul_f32_e32 v9, 0xbfb8aa3b, v26
	v_exp_f32_e32 v9, v9
	v_pk_mul_f32 v[4:5], v[10:11], v[4:5] op_sel_hi:[0,1]
	v_add_f32_e32 v9, 1.0, v9
	v_rcp_f32_e32 v28, v9
	v_mul_f32_e32 v9, 0xbfb8aa3b, v27
	v_exp_f32_e32 v9, v9
	s_nop 0
	v_add_f32_e32 v9, 1.0, v9
	v_rcp_f32_e32 v29, v9
	v_pk_fma_f32 v[4:5], v[8:9], v[24:25], v[4:5] op_sel_hi:[0,1,1]
	v_pk_fma_f32 v[4:5], v[12:13], v[20:21], v[4:5] op_sel_hi:[0,1,1]
	v_pk_fma_f32 v[4:5], v[14:15], v[22:23], v[4:5] op_sel_hi:[0,1,1]
	v_pk_mul_f32 v[26:27], v[26:27], v[28:29]
	s_nop 0
	v_pk_mul_f32 v[152:153], v[6:7], v[26:27]
	v_mul_f32_e32 v6, 0xbfb8aa3b, v4
	v_mul_f32_e32 v7, 0xbfb8aa3b, v5
	v_exp_f32_e32 v6, v6
	v_exp_f32_e32 v7, v7
	v_add_f32_e32 v6, 1.0, v6
	v_add_f32_e32 v7, 1.0, v7
	v_rcp_f32_e32 v6, v6
	v_rcp_f32_e32 v7, v7
	s_nop 0
	v_pk_mul_f32 v[4:5], v[4:5], v[6:7]
	s_nop 0
	v_pk_mul_f32 v[154:155], v[0:1], v[4:5]
	v_pk_mul_f32 v[0:1], v[10:11], v[22:23] op_sel_hi:[0,1]
	v_pk_fma_f32 v[0:1], v[8:9], v[20:21], v[0:1] op_sel_hi:[0,1,1]
	v_pk_fma_f32 v[0:1], v[12:13], v[16:17], v[0:1] op_sel_hi:[0,1,1]
	v_pk_fma_f32 v[0:1], v[14:15], v[18:19], v[0:1] op_sel_hi:[0,1,1]
	v_mul_f32_e32 v4, 0xbfb8aa3b, v0
	v_mul_f32_e32 v5, 0xbfb8aa3b, v1
	v_exp_f32_e32 v4, v4
	v_exp_f32_e32 v5, v5
	v_add_f32_e32 v4, 1.0, v4
	v_add_f32_e32 v5, 1.0, v5
	v_rcp_f32_e32 v4, v4
	v_rcp_f32_e32 v5, v5
	s_nop 0
	v_pk_mul_f32 v[0:1], v[0:1], v[4:5]
	s_nop 0
	v_pk_mul_f32 v[156:157], v[2:3], v[0:1]
	ds_read_u16 v0, v205 offset:26880
	ds_read_u16 v1, v205 offset:27648
	s_waitcnt lgkmcnt(1)
; __device__ __forceinline__ float bf2f(u16 h) { return __uint_as_float(((unsigned)h) << 16); }
; __device__ __forceinline__ float siluf_(float x) { return x * __builtin_amdgcn_rcpf(1.f + __expf(-x)); }
; __device__ __forceinline__ void gdn_chunk_item(const Params& p, int item, char* smem) {
;     ...
; #pragma unroll
;     for (int t = 0; t < 64; t++) {
;       float x3 = bf2f(tp[(t + 3) * 384]);
;       float cv = x0 * w0 + x1 * w1 + x2 * w2 + x3 * w3;
;       vv[t] = siluf_(cv) * sm_bt[t];
;       x0 = x1; x1 = x2; x2 = x3;
;     }
	v_lshlrev_b32_e32 v4, 16, v0
	s_waitcnt lgkmcnt(0)
	v_lshlrev_b32_e32 v5, 16, v1
	v_pk_mul_f32 v[0:1], v[10:11], v[18:19] op_sel_hi:[0,1]
	v_pk_fma_f32 v[0:1], v[8:9], v[16:17], v[0:1] op_sel_hi:[0,1,1]
	v_pk_mov_b32 v[6:7], v[18:19], v[4:5] op_sel:[1,0]
	s_nop 0
	v_pk_fma_f32 v[0:1], v[12:13], v[6:7], v[0:1] op_sel_hi:[0,1,1]
	v_pk_fma_f32 v[0:1], v[14:15], v[4:5], v[0:1] op_sel_hi:[0,1,1]
	v_mul_f32_e32 v2, 0xbfb8aa3b, v0
	v_mul_f32_e32 v3, 0xbfb8aa3b, v1
	v_exp_f32_e32 v2, v2
	v_exp_f32_e32 v3, v3
	v_add_f32_e32 v2, 1.0, v2
	v_add_f32_e32 v3, 1.0, v3
	v_rcp_f32_e32 v2, v2
	v_rcp_f32_e32 v3, v3
	s_nop 0
	v_pk_mul_f32 v[16:17], v[0:1], v[2:3]
	ds_read_b128 v[0:3], v35 offset:64896
	s_waitcnt lgkmcnt(0)
	v_pk_mul_f32 v[158:159], v[0:1], v[16:17]
	ds_read_u16 v0, v205 offset:28416
	ds_read_u16 v1, v205 offset:29184
	v_pk_mul_f32 v[16:17], v[10:11], v[4:5] op_sel_hi:[0,1]
	v_pk_fma_f32 v[6:7], v[8:9], v[6:7], v[16:17] op_sel_hi:[0,1,1]
	s_waitcnt lgkmcnt(1)
	v_lshlrev_b32_e32 v0, 16, v0
	s_waitcnt lgkmcnt(0)
	v_lshlrev_b32_e32 v1, 16, v1
	v_pk_mov_b32 v[16:17], v[4:5], v[0:1] op_sel:[1,0]
	s_nop 0
	v_pk_fma_f32 v[4:5], v[12:13], v[16:17], v[6:7] op_sel_hi:[0,1,1]
	v_pk_fma_f32 v[4:5], v[14:15], v[0:1], v[4:5] op_sel_hi:[0,1,1]
	v_mul_f32_e32 v6, 0xbfb8aa3b, v4
	v_mul_f32_e32 v7, 0xbfb8aa3b, v5
	v_exp_f32_e32 v6, v6
	v_exp_f32_e32 v7, v7
	v_add_f32_e32 v6, 1.0, v6
	v_add_f32_e32 v7, 1.0, v7
	v_rcp_f32_e32 v6, v6
	v_rcp_f32_e32 v7, v7
	s_nop 0
	v_pk_mul_f32 v[4:5], v[4:5], v[6:7]
	s_nop 0
	v_pk_mul_f32 v[160:161], v[2:3], v[4:5]
	ds_read_u16 v2, v205 offset:29952
	ds_read_u16 v3, v205 offset:30720
	s_waitcnt lgkmcnt(1)
	v_lshlrev_b32_e32 v4, 16, v2
	s_waitcnt lgkmcnt(0)
	v_lshlrev_b32_e32 v5, 16, v3
	v_pk_mul_f32 v[2:3], v[10:11], v[0:1] op_sel_hi:[0,1]
	v_pk_fma_f32 v[2:3], v[8:9], v[16:17], v[2:3] op_sel_hi:[0,1,1]
	v_pk_mov_b32 v[6:7], v[0:1], v[4:5] op_sel:[1,0]
	s_nop 0
	v_pk_fma_f32 v[0:1], v[12:13], v[6:7], v[2:3] op_sel_hi:[0,1,1]
	v_pk_fma_f32 v[0:1], v[14:15], v[4:5], v[0:1] op_sel_hi:[0,1,1]
	v_mul_f32_e32 v2, 0xbfb8aa3b, v0
	v_mul_f32_e32 v3, 0xbfb8aa3b, v1
	v_exp_f32_e32 v2, v2
	v_exp_f32_e32 v3, v3
	v_add_f32_e32 v2, 1.0, v2
	v_add_f32_e32 v3, 1.0, v3
	v_rcp_f32_e32 v2, v2
	v_rcp_f32_e32 v3, v3
	s_nop 0
	v_pk_mul_f32 v[16:17], v[0:1], v[2:3]
	ds_read_b128 v[0:3], v35 offset:64912
	s_waitcnt lgkmcnt(0)
	v_pk_mul_f32 v[162:163], v[0:1], v[16:17]
	ds_read_u16 v0, v205 offset:31488
	ds_read_u16 v1, v205 offset:32256
	v_pk_mul_f32 v[16:17], v[10:11], v[4:5] op_sel_hi:[0,1]
	v_pk_fma_f32 v[6:7], v[8:9], v[6:7], v[16:17] op_sel_hi:[0,1,1]
	s_waitcnt lgkmcnt(1)
	v_lshlrev_b32_e32 v0, 16, v0
	s_waitcnt lgkmcnt(0)
	v_lshlrev_b32_e32 v1, 16, v1
	v_pk_mov_b32 v[4:5], v[4:5], v[0:1] op_sel:[1,0]
	s_nop 0
	v_pk_fma_f32 v[6:7], v[12:13], v[4:5], v[6:7] op_sel_hi:[0,1,1]
	v_pk_fma_f32 v[6:7], v[14:15], v[0:1], v[6:7] op_sel_hi:[0,1,1]
	v_mul_f32_e32 v9, 0xbfb8aa3b, v6
	v_exp_f32_e32 v9, v9
	s_nop 0
	v_add_f32_e32 v9, 1.0, v9
	v_rcp_f32_e32 v16, v9
	v_mul_f32_e32 v9, 0xbfb8aa3b, v7
	v_exp_f32_e32 v9, v9
	s_nop 0
	v_add_f32_e32 v9, 1.0, v9
	v_rcp_f32_e32 v17, v9
	s_nop 0
	v_pk_mul_f32 v[6:7], v[6:7], v[16:17]
	s_nop 0
	v_pk_mul_f32 v[164:165], v[2:3], v[6:7]
	ds_read_u16 v2, v205 offset:33024
	ds_read_u16 v3, v205 offset:33792
	s_waitcnt lgkmcnt(1)
	v_lshlrev_b32_e32 v6, 16, v2
	s_waitcnt lgkmcnt(0)
	v_lshlrev_b32_e32 v7, 16, v3
	v_pk_mul_f32 v[2:3], v[10:11], v[0:1] op_sel_hi:[0,1]
	v_pk_fma_f32 v[2:3], v[8:9], v[4:5], v[2:3] op_sel_hi:[0,1,1]
	v_pk_mov_b32 v[4:5], v[0:1], v[6:7] op_sel:[1,0]
	s_nop 0
	v_pk_fma_f32 v[0:1], v[12:13], v[4:5], v[2:3] op_sel_hi:[0,1,1]
	v_pk_fma_f32 v[0:1], v[14:15], v[6:7], v[0:1] op_sel_hi:[0,1,1]
	v_mul_f32_e32 v2, 0xbfb8aa3b, v0
	v_mul_f32_e32 v3, 0xbfb8aa3b, v1
	v_exp_f32_e32 v2, v2
	v_exp_f32_e32 v3, v3
	v_add_f32_e32 v2, 1.0, v2
	v_add_f32_e32 v3, 1.0, v3
	v_rcp_f32_e32 v2, v2
	v_rcp_f32_e32 v3, v3
	s_nop 0
	v_pk_mul_f32 v[16:17], v[0:1], v[2:3]
	ds_read_b128 v[0:3], v35 offset:64928
	s_waitcnt lgkmcnt(0)
	v_pk_mul_f32 v[166:167], v[0:1], v[16:17]
	ds_read_u16 v0, v205 offset:34560
	ds_read_u16 v1, v205 offset:35328
	v_pk_mul_f32 v[16:17], v[10:11], v[6:7] op_sel_hi:[0,1]
	v_pk_fma_f32 v[4:5], v[8:9], v[4:5], v[16:17] op_sel_hi:[0,1,1]
	s_waitcnt lgkmcnt(1)
	v_lshlrev_b32_e32 v0, 16, v0
	s_waitcnt lgkmcnt(0)
	v_lshlrev_b32_e32 v1, 16, v1
	v_pk_mov_b32 v[6:7], v[6:7], v[0:1] op_sel:[1,0]
	s_nop 0
	v_pk_fma_f32 v[4:5], v[12:13], v[6:7], v[4:5] op_sel_hi:[0,1,1]
	v_pk_fma_f32 v[4:5], v[14:15], v[0:1], v[4:5] op_sel_hi:[0,1,1]
	v_mul_f32_e32 v9, 0xbfb8aa3b, v4
	v_exp_f32_e32 v9, v9
	s_nop 0
	v_add_f32_e32 v9, 1.0, v9
	v_rcp_f32_e32 v16, v9
	v_mul_f32_e32 v9, 0xbfb8aa3b, v5
	v_exp_f32_e32 v9, v9
	s_nop 0
	v_add_f32_e32 v9, 1.0, v9
	v_rcp_f32_e32 v17, v9
	s_nop 0
	v_pk_mul_f32 v[4:5], v[4:5], v[16:17]
	s_nop 0
	v_pk_mul_f32 v[168:169], v[2:3], v[4:5]
	ds_read_u16 v2, v205 offset:36096
	ds_read_u16 v3, v205 offset:36864
	s_waitcnt lgkmcnt(1)
	v_lshlrev_b32_e32 v4, 16, v2
	s_waitcnt lgkmcnt(0)
	v_lshlrev_b32_e32 v5, 16, v3
	v_pk_mul_f32 v[2:3], v[10:11], v[0:1] op_sel_hi:[0,1]
	v_pk_fma_f32 v[2:3], v[8:9], v[6:7], v[2:3] op_sel_hi:[0,1,1]
	v_pk_mov_b32 v[6:7], v[0:1], v[4:5] op_sel:[1,0]
	s_nop 0
	v_pk_fma_f32 v[0:1], v[12:13], v[6:7], v[2:3] op_sel_hi:[0,1,1]
	v_pk_fma_f32 v[0:1], v[14:15], v[4:5], v[0:1] op_sel_hi:[0,1,1]
	v_mul_f32_e32 v2, 0xbfb8aa3b, v0
	v_mul_f32_e32 v3, 0xbfb8aa3b, v1
	v_exp_f32_e32 v2, v2
	v_exp_f32_e32 v3, v3
	v_add_f32_e32 v2, 1.0, v2
	v_add_f32_e32 v3, 1.0, v3
	v_rcp_f32_e32 v2, v2
	v_rcp_f32_e32 v3, v3
	s_nop 0
	v_pk_mul_f32 v[16:17], v[0:1], v[2:3]
	ds_read_b128 v[0:3], v35 offset:64944
	s_waitcnt lgkmcnt(0)
; __device__ __forceinline__ float bf2f(u16 h) { return __uint_as_float(((unsigned)h) << 16); }
; __device__ __forceinline__ float siluf_(float x) { return x * __builtin_amdgcn_rcpf(1.f + __expf(-x)); }
; __device__ __forceinline__ void gdn_chunk_item(const Params& p, int item, char* smem) {
;     ...
; #pragma unroll
;     for (int t = 0; t < 64; t++) {
;       float x3 = bf2f(tp[(t + 3) * 384]);
;       float cv = x0 * w0 + x1 * w1 + x2 * w2 + x3 * w3;
;       vv[t] = siluf_(cv) * sm_bt[t];
;       x0 = x1; x1 = x2; x2 = x3;
;     }
	v_pk_mul_f32 v[170:171], v[0:1], v[16:17]
	ds_read_u16 v0, v205 offset:37632
	ds_read_u16 v1, v205 offset:38400
	v_pk_mul_f32 v[16:17], v[10:11], v[4:5] op_sel_hi:[0,1]
	v_pk_fma_f32 v[6:7], v[8:9], v[6:7], v[16:17] op_sel_hi:[0,1,1]
	s_waitcnt lgkmcnt(1)
	v_lshlrev_b32_e32 v0, 16, v0
	s_waitcnt lgkmcnt(0)
	v_lshlrev_b32_e32 v1, 16, v1
	v_pk_mov_b32 v[4:5], v[4:5], v[0:1] op_sel:[1,0]
	s_nop 0
	v_pk_fma_f32 v[6:7], v[12:13], v[4:5], v[6:7] op_sel_hi:[0,1,1]
	v_pk_fma_f32 v[6:7], v[14:15], v[0:1], v[6:7] op_sel_hi:[0,1,1]
	v_mul_f32_e32 v9, 0xbfb8aa3b, v6
	v_exp_f32_e32 v9, v9
	s_nop 0
	v_add_f32_e32 v9, 1.0, v9
	v_rcp_f32_e32 v16, v9
	v_mul_f32_e32 v9, 0xbfb8aa3b, v7
	v_exp_f32_e32 v9, v9
	s_nop 0
	v_add_f32_e32 v9, 1.0, v9
	v_rcp_f32_e32 v17, v9
	s_nop 0
	v_pk_mul_f32 v[6:7], v[6:7], v[16:17]
	s_nop 0
	v_pk_mul_f32 v[172:173], v[2:3], v[6:7]
	ds_read_u16 v2, v205 offset:39168
	ds_read_u16 v3, v205 offset:39936
	s_waitcnt lgkmcnt(1)
	v_lshlrev_b32_e32 v6, 16, v2
	s_waitcnt lgkmcnt(0)
	v_lshlrev_b32_e32 v7, 16, v3
	v_pk_mul_f32 v[2:3], v[10:11], v[0:1] op_sel_hi:[0,1]
	v_pk_fma_f32 v[2:3], v[8:9], v[4:5], v[2:3] op_sel_hi:[0,1,1]
	v_pk_mov_b32 v[4:5], v[0:1], v[6:7] op_sel:[1,0]
	s_nop 0
	v_pk_fma_f32 v[0:1], v[12:13], v[4:5], v[2:3] op_sel_hi:[0,1,1]
	v_pk_fma_f32 v[0:1], v[14:15], v[6:7], v[0:1] op_sel_hi:[0,1,1]
	v_mul_f32_e32 v2, 0xbfb8aa3b, v0
	v_mul_f32_e32 v3, 0xbfb8aa3b, v1
	v_exp_f32_e32 v2, v2
	v_exp_f32_e32 v3, v3
	v_add_f32_e32 v2, 1.0, v2
	v_add_f32_e32 v3, 1.0, v3
	v_rcp_f32_e32 v2, v2
	v_rcp_f32_e32 v3, v3
	s_nop 0
	v_pk_mul_f32 v[16:17], v[0:1], v[2:3]
	ds_read_b128 v[0:3], v35 offset:64960
	s_waitcnt lgkmcnt(0)
	v_pk_mul_f32 v[174:175], v[0:1], v[16:17]
	ds_read_u16 v0, v205 offset:40704
	ds_read_u16 v1, v205 offset:41472
	v_pk_mul_f32 v[16:17], v[10:11], v[6:7] op_sel_hi:[0,1]
	v_pk_fma_f32 v[4:5], v[8:9], v[4:5], v[16:17] op_sel_hi:[0,1,1]
	s_waitcnt lgkmcnt(1)
	v_lshlrev_b32_e32 v0, 16, v0
	s_waitcnt lgkmcnt(0)
	v_lshlrev_b32_e32 v1, 16, v1
	v_pk_mov_b32 v[6:7], v[6:7], v[0:1] op_sel:[1,0]
	s_nop 0
	v_pk_fma_f32 v[4:5], v[12:13], v[6:7], v[4:5] op_sel_hi:[0,1,1]
	v_pk_fma_f32 v[4:5], v[14:15], v[0:1], v[4:5] op_sel_hi:[0,1,1]
	v_mul_f32_e32 v9, 0xbfb8aa3b, v4
	v_exp_f32_e32 v9, v9
	s_nop 0
	v_add_f32_e32 v9, 1.0, v9
	v_rcp_f32_e32 v16, v9
	v_mul_f32_e32 v9, 0xbfb8aa3b, v5
	v_exp_f32_e32 v9, v9
	s_nop 0
	v_add_f32_e32 v9, 1.0, v9
	v_rcp_f32_e32 v17, v9
	s_nop 0
	v_pk_mul_f32 v[4:5], v[4:5], v[16:17]
	s_nop 0
	v_pk_mul_f32 v[178:179], v[2:3], v[4:5]
	ds_read_u16 v2, v205 offset:42240
	ds_read_u16 v3, v205 offset:43008
	s_waitcnt lgkmcnt(1)
	v_lshlrev_b32_e32 v4, 16, v2
	s_waitcnt lgkmcnt(0)
	v_lshlrev_b32_e32 v5, 16, v3
	v_pk_mul_f32 v[2:3], v[10:11], v[0:1] op_sel_hi:[0,1]
	v_pk_fma_f32 v[2:3], v[8:9], v[6:7], v[2:3] op_sel_hi:[0,1,1]
	v_pk_mov_b32 v[6:7], v[0:1], v[4:5] op_sel:[1,0]
	s_nop 0
	v_pk_fma_f32 v[0:1], v[12:13], v[6:7], v[2:3] op_sel_hi:[0,1,1]
	v_pk_fma_f32 v[0:1], v[14:15], v[4:5], v[0:1] op_sel_hi:[0,1,1]
	v_mul_f32_e32 v2, 0xbfb8aa3b, v0
	v_mul_f32_e32 v3, 0xbfb8aa3b, v1
	v_exp_f32_e32 v2, v2
	v_exp_f32_e32 v3, v3
	v_add_f32_e32 v2, 1.0, v2
	v_add_f32_e32 v3, 1.0, v3
	v_rcp_f32_e32 v2, v2
	v_rcp_f32_e32 v3, v3
	s_nop 0
	v_pk_mul_f32 v[16:17], v[0:1], v[2:3]
	ds_read_b128 v[0:3], v35 offset:64976
	s_waitcnt lgkmcnt(0)
	v_pk_mul_f32 v[180:181], v[0:1], v[16:17]
	ds_read_u16 v0, v205 offset:43776
	ds_read_u16 v1, v205 offset:44544
	s_waitcnt lgkmcnt(1)
	v_lshlrev_b32_e32 v16, 16, v0
	s_waitcnt lgkmcnt(0)
; __device__ __forceinline__ float bf2f(u16 h) { return __uint_as_float(((unsigned)h) << 16); }
; __device__ __forceinline__ float siluf_(float x) { return x * __builtin_amdgcn_rcpf(1.f + __expf(-x)); }
; __device__ __forceinline__ void gdn_chunk_item(const Params& p, int item, char* smem) {
;     ...
; #pragma unroll
;     for (int t = 0; t < 64; t++) {
;       float x3 = bf2f(tp[(t + 3) * 384]);
;       float cv = x0 * w0 + x1 * w1 + x2 * w2 + x3 * w3;
;       vv[t] = siluf_(cv) * sm_bt[t];
;       x0 = x1; x1 = x2; x2 = x3;
;     }
	v_lshlrev_b32_e32 v17, 16, v1
	v_pk_mul_f32 v[0:1], v[10:11], v[4:5] op_sel_hi:[0,1]
	v_pk_fma_f32 v[0:1], v[8:9], v[6:7], v[0:1] op_sel_hi:[0,1,1]
	v_pk_mov_b32 v[4:5], v[4:5], v[16:17] op_sel:[1,0]
	v_mov_b32_e32 v18, v17
	v_pk_fma_f32 v[0:1], v[12:13], v[4:5], v[0:1] op_sel_hi:[0,1,1]
	v_pk_fma_f32 v[0:1], v[14:15], v[16:17], v[0:1] op_sel_hi:[0,1,1]
	v_mul_f32_e32 v6, 0xbfb8aa3b, v0
	v_mul_f32_e32 v7, 0xbfb8aa3b, v1
	v_exp_f32_e32 v6, v6
	v_exp_f32_e32 v7, v7
	v_add_f32_e32 v6, 1.0, v6
	v_add_f32_e32 v7, 1.0, v7
	v_rcp_f32_e32 v6, v6
	v_rcp_f32_e32 v7, v7
	s_nop 0
	v_pk_mul_f32 v[0:1], v[0:1], v[6:7]
	s_nop 0
	v_pk_mul_f32 v[184:185], v[2:3], v[0:1]
	ds_read_u16 v0, v205 offset:45312
	s_waitcnt lgkmcnt(0)
	v_lshlrev_b32_e32 v19, 16, v0
	ds_read_u16 v0, v205 offset:46080
	ds_read_u16 v1, v205 offset:46848
	v_mov_b32_e32 v2, v19
	s_waitcnt lgkmcnt(1)
	v_lshlrev_b32_e32 v20, 16, v0
	ds_read_u16 v0, v205 offset:47616
	s_waitcnt lgkmcnt(1)
	v_lshlrev_b32_e32 v21, 16, v1
	v_mov_b32_e32 v3, v20
	v_mov_b32_e32 v22, v21
	s_waitcnt lgkmcnt(0)
	v_lshlrev_b32_e32 v23, 16, v0
	v_pk_mul_f32 v[0:1], v[10:11], v[16:17] op_sel_hi:[0,1]
	v_pk_fma_f32 v[0:1], v[8:9], v[4:5], v[0:1] op_sel_hi:[0,1,1]
	v_pk_fma_f32 v[0:1], v[12:13], v[18:19], v[0:1] op_sel_hi:[0,1,1]
	v_pk_fma_f32 v[4:5], v[14:15], v[2:3], v[0:1] op_sel_hi:[0,1,1]
	v_mul_f32_e32 v0, 0xbfb8aa3b, v4
	v_mul_f32_e32 v7, 0xbfb8aa3b, v5
	v_exp_f32_e32 v0, v0
	v_exp_f32_e32 v7, v7
	v_mov_b32_e32 v11, v8
	v_mov_b32_e32 v16, v20
	v_add_f32_e32 v0, 1.0, v0
	v_add_f32_e32 v7, 1.0, v7
	v_rcp_f32_e32 v6, v0
	ds_read_b128 v[0:3], v35 offset:64992
	v_rcp_f32_e32 v7, v7
	v_pk_mul_f32 v[16:17], v[10:11], v[16:17]
	v_pk_mul_f32 v[4:5], v[4:5], v[6:7]
	s_waitcnt lgkmcnt(0)
	v_pk_mul_f32 v[186:187], v[0:1], v[4:5]
	ds_read_u16 v0, v205 offset:49152
	ds_read_u16 v1, v205 offset:48384
	v_mov_b32_e32 v4, v23
	s_waitcnt lgkmcnt(1)
	v_lshlrev_b32_e32 v7, 16, v0
	v_mov_b32_e32 v0, v19
	s_waitcnt lgkmcnt(0)
	v_lshlrev_b32_e32 v5, 16, v1
	v_pk_fma_f32 v[0:1], v[10:11], v[0:1], v[16:17] op_sel:[0,0,1] op_sel_hi:[1,0,0]
	v_mov_b32_e32 v6, v5
	v_pk_fma_f32 v[0:1], v[12:13], v[20:21], v[0:1] op_sel_hi:[0,1,1]
	v_pk_fma_f32 v[0:1], v[14:15], v[22:23], v[0:1] op_sel_hi:[0,1,1]
	v_mul_f32_e32 v9, 0xbfb8aa3b, v0
	v_exp_f32_e32 v9, v9
	s_nop 0
	v_add_f32_e32 v9, 1.0, v9
	v_rcp_f32_e32 v16, v9
	v_mul_f32_e32 v9, 0xbfb8aa3b, v1
	v_exp_f32_e32 v9, v9
	s_nop 0
	v_add_f32_e32 v9, 1.0, v9
	v_rcp_f32_e32 v17, v9
	s_nop 0
	v_pk_mul_f32 v[0:1], v[0:1], v[16:17]
	s_nop 0
	v_pk_mul_f32 v[188:189], v[2:3], v[0:1]
	v_pk_mul_f32 v[0:1], v[10:11], v[22:23] op_sel_hi:[0,1]
	v_pk_fma_f32 v[0:1], v[8:9], v[20:21], v[0:1] op_sel_hi:[0,1,1]
	v_pk_fma_f32 v[0:1], v[12:13], v[4:5], v[0:1] op_sel_hi:[0,1,1]
	v_pk_fma_f32 v[0:1], v[14:15], v[6:7], v[0:1] op_sel_hi:[0,1,1]
	v_mul_f32_e32 v2, 0xbfb8aa3b, v0
	v_mul_f32_e32 v3, 0xbfb8aa3b, v1
	v_exp_f32_e32 v2, v2
	v_exp_f32_e32 v3, v3
	v_pk_mul_f32 v[10:11], v[10:11], v[6:7] op_sel_hi:[0,1]
	v_pk_fma_f32 v[4:5], v[8:9], v[4:5], v[10:11] op_sel_hi:[0,1,1]
	v_add_f32_e32 v2, 1.0, v2
	v_add_f32_e32 v3, 1.0, v3
	v_rcp_f32_e32 v2, v2
	v_rcp_f32_e32 v3, v3
	s_nop 0
	v_pk_mul_f32 v[16:17], v[0:1], v[2:3]
	ds_read_b128 v[0:3], v35 offset:65008
	s_waitcnt lgkmcnt(0)
	v_pk_mul_f32 v[182:183], v[0:1], v[16:17]
	ds_read_u16 v1, v205 offset:50688
	ds_read_u16 v0, v205 offset:49920
	s_waitcnt lgkmcnt(1)
	v_lshlrev_b32_e32 v1, 16, v1
	s_waitcnt lgkmcnt(0)
	v_lshlrev_b32_e32 v0, 16, v0
	v_pk_mov_b32 v[6:7], v[6:7], v[0:1] op_sel:[1,0]
	s_nop 0
	v_pk_fma_f32 v[4:5], v[12:13], v[6:7], v[4:5] op_sel_hi:[0,1,1]
	v_pk_fma_f32 v[0:1], v[14:15], v[0:1], v[4:5] op_sel_hi:[0,1,1]
	v_mul_f32_e32 v4, 0xbfb8aa3b, v0
	v_mul_f32_e32 v5, 0xbfb8aa3b, v1
	v_exp_f32_e32 v4, v4
	v_exp_f32_e32 v5, v5
	v_add_f32_e32 v4, 1.0, v4
	v_add_f32_e32 v5, 1.0, v5
	v_rcp_f32_e32 v4, v4
	v_rcp_f32_e32 v5, v5
	s_nop 0
	v_pk_mul_f32 v[0:1], v[0:1], v[4:5]
	s_nop 0
	v_pk_mul_f32 v[190:191], v[2:3], v[0:1]
